# phase 1: blocks<128 run filter units first, then prenorm + transposes; blocks>=128 prenorm + transposes first
# speedup vs baseline: 1.0085x; 1.0026x over previous
.LBB0_223:
.LBB0_224:
	s_cmp_lt_u32 s96, 128
	s_cbranch_scc1 .Ltrp1_A_skip
	s_waitcnt vmcnt(0) lgkmcnt(0)
	s_load_dwordx2 s[0:1], s[92:93], 0x40
	s_load_dwordx2 s[2:3], s[92:93], 0x38
	s_load_dwordx2 s[4:5], s[92:93], 0xf0
	s_load_dwordx2 s[6:7], s[92:93], 0x0
	s_load_dwordx2 s[8:9], s[92:93], 0x8
	v_and_b32_e32 v2, 63, v154
	v_lshlrev_b32_e32 v1, 4, v2
	v_lshlrev_b32_e32 v2, 3, v2
	v_mov_b32_e32 v6, 1.0
	v_mov_b32_e32 v7, 1.0
	s_mov_b32 s40, 0x3a000000
	s_mov_b32 s41, 0x358637bd
	v_readfirstlane_b32 s10, v154
	s_lshr_b32 s10, s10, 6
	s_lshl_b32 s12, s96, 3
	s_add_u32 s10, s10, s12
	s_waitcnt lgkmcnt(0)
	s_add_u32 s12, s10, 0
	s_lshl_b32 s13, s12, 13
	s_lshl_b32 s14, s12, 12
	s_add_u32 s20, s6, s13
	s_addc_u32 s21, s7, 0
	s_add_u32 s22, s90, 0x21918000
	s_addc_u32 s23, s91, 0
	s_add_u32 s22, s22, s14
	s_addc_u32 s23, s23, 0
	s_add_u32 s36, s20, 0x1000
	s_addc_u32 s37, s21, 0
	global_load_dwordx4 v[34:37], v1, s[20:21] nt
	global_load_dwordx4 v[38:41], v1, s[20:21] offset:1024 nt
	global_load_dwordx4 v[42:45], v1, s[20:21] offset:2048 nt
	global_load_dwordx4 v[46:49], v1, s[20:21] offset:3072 nt
	global_load_dwordx4 v[50:53], v1, s[36:37] nt
	global_load_dwordx4 v[54:57], v1, s[36:37] offset:1024 nt
	global_load_dwordx4 v[58:61], v1, s[36:37] offset:2048 nt
	global_load_dwordx4 v[62:65], v1, s[36:37] offset:3072 nt
	s_mov_b32 s16, 4
	s_add_u32 s17, s16, 0
	s_mul_i32 s17, s17, 49152
	s_add_u32 s17, s17, 0x10404000
	s_add_u32 s28, s90, s17
	s_addc_u32 s29, s91, 0
	s_add_u32 s17, s16, 0
	s_mul_i32 s17, s17, 49152
	s_add_u32 s17, s17, 0x10400000
	s_add_u32 s30, s90, s17
	s_addc_u32 s31, s91, 0
	s_add_u32 s32, s30, 0x2000
	s_addc_u32 s33, s31, 0
	s_add_u32 s18, s2, 0x1000
	s_addc_u32 s19, s3, 0
	global_load_dwordx4 v[130:133], v1, s[2:3]
	global_load_dwordx4 v[134:137], v1, s[2:3] offset:1024
	global_load_dwordx4 v[138:141], v1, s[2:3] offset:2048
	global_load_dwordx4 v[142:145], v1, s[2:3] offset:3072
	global_load_dwordx4 v[146:149], v1, s[18:19]
	global_load_dwordx4 v[150:153], v1, s[18:19] offset:1024
	global_load_dwordx4 v[156:159], v1, s[18:19] offset:2048
	global_load_dwordx4 v[160:163], v1, s[18:19] offset:3072
	s_add_u32 s18, s30, 0x1000
	s_addc_u32 s19, s31, 0
	global_load_dwordx4 v[164:167], v1, s[30:31]
	global_load_dwordx4 v[168:171], v1, s[30:31] offset:1024
	global_load_dwordx4 v[172:175], v1, s[30:31] offset:2048
	global_load_dwordx4 v[176:179], v1, s[30:31] offset:3072
	global_load_dwordx4 v[180:183], v1, s[18:19]
	global_load_dwordx4 v[184:187], v1, s[18:19] offset:1024
	global_load_dwordx4 v[188:191], v1, s[18:19] offset:2048
	global_load_dwordx4 v[192:195], v1, s[18:19] offset:3072
	s_add_u32 s18, s32, 0x1000
	s_addc_u32 s19, s33, 0
	global_load_dwordx4 v[196:199], v1, s[32:33]
	global_load_dwordx4 v[200:203], v1, s[32:33] offset:1024
	global_load_dwordx4 v[204:207], v1, s[32:33] offset:2048
	global_load_dwordx4 v[208:211], v1, s[32:33] offset:3072
	global_load_dwordx4 v[212:215], v1, s[18:19]
	global_load_dwordx4 v[216:219], v1, s[18:19] offset:1024
	global_load_dwordx4 v[220:223], v1, s[18:19] offset:2048
	global_load_dwordx4 v[224:227], v1, s[18:19] offset:3072
	s_add_u32 s12, s10, 2048
	s_lshl_b32 s13, s12, 13
	s_lshl_b32 s14, s12, 12
	s_add_u32 s20, s6, s13
	s_addc_u32 s21, s7, 0
	s_add_u32 s22, s90, 0x21918000
	s_addc_u32 s23, s91, 0
	s_add_u32 s22, s22, s14
	s_addc_u32 s23, s23, 0
	s_add_u32 s36, s20, 0x1000
	s_addc_u32 s37, s21, 0
	global_load_dwordx4 v[66:69], v1, s[20:21] nt
	global_load_dwordx4 v[70:73], v1, s[20:21] offset:1024 nt
	global_load_dwordx4 v[74:77], v1, s[20:21] offset:2048 nt
	global_load_dwordx4 v[78:81], v1, s[20:21] offset:3072 nt
	global_load_dwordx4 v[82:85], v1, s[36:37] nt
	global_load_dwordx4 v[86:89], v1, s[36:37] offset:1024 nt
	global_load_dwordx4 v[90:93], v1, s[36:37] offset:2048 nt
	global_load_dwordx4 v[94:97], v1, s[36:37] offset:3072 nt
	s_add_u32 s12, s10, 0
	s_lshl_b32 s14, s12, 12
	s_add_u32 s26, s90, 0x11918000
	s_addc_u32 s27, s91, 0
	s_add_u32 s26, s26, s14
	s_addc_u32 s27, s27, 0
	s_waitcnt vmcnt(32)
	v_mov_b32_e32 v8, 0
	v_fmac_f32_e32 v8, v34, v34
	v_fmac_f32_e32 v8, v35, v35
	v_fmac_f32_e32 v8, v36, v36
	v_fmac_f32_e32 v8, v37, v37
	v_fmac_f32_e32 v8, v38, v38
	v_fmac_f32_e32 v8, v39, v39
	v_fmac_f32_e32 v8, v40, v40
	v_fmac_f32_e32 v8, v41, v41
	v_fmac_f32_e32 v8, v42, v42
	v_fmac_f32_e32 v8, v43, v43
	v_fmac_f32_e32 v8, v44, v44
	v_fmac_f32_e32 v8, v45, v45
	v_fmac_f32_e32 v8, v46, v46
	v_fmac_f32_e32 v8, v47, v47
	v_fmac_f32_e32 v8, v48, v48
	v_fmac_f32_e32 v8, v49, v49
	v_fmac_f32_e32 v8, v50, v50
	v_fmac_f32_e32 v8, v51, v51
	v_fmac_f32_e32 v8, v52, v52
	v_fmac_f32_e32 v8, v53, v53
	v_fmac_f32_e32 v8, v54, v54
	v_fmac_f32_e32 v8, v55, v55
	v_fmac_f32_e32 v8, v56, v56
	v_fmac_f32_e32 v8, v57, v57
	v_fmac_f32_e32 v8, v58, v58
	v_fmac_f32_e32 v8, v59, v59
	v_fmac_f32_e32 v8, v60, v60
	v_fmac_f32_e32 v8, v61, v61
	v_fmac_f32_e32 v8, v62, v62
	v_fmac_f32_e32 v8, v63, v63
	v_fmac_f32_e32 v8, v64, v64
	v_fmac_f32_e32 v8, v65, v65
	s_nop 1
	v_add_f32_dpp v8, v8, v8 quad_perm:[1,0,3,2] row_mask:0xf bank_mask:0xf
	s_nop 1
	v_add_f32_dpp v8, v8, v8 quad_perm:[2,3,0,1] row_mask:0xf bank_mask:0xf
	s_nop 1
	v_add_f32_dpp v8, v8, v8 row_ror:4 row_mask:0xf bank_mask:0xf
	s_nop 1
	v_add_f32_dpp v8, v8, v8 row_ror:8 row_mask:0xf bank_mask:0xf
	s_nop 1
	v_readlane_b32 s42, v8, 0
	v_readlane_b32 s43, v8, 16
	v_readlane_b32 s44, v8, 32
	v_readlane_b32 s45, v8, 48
	s_nop 1
	v_mov_b32_e32 v8, s42
	v_add_f32_e32 v8, s43, v8
	v_add_f32_e32 v8, s44, v8
	v_add_f32_e32 v8, s45, v8
	v_mov_b32_e32 v4, s41
	v_fmac_f32_e32 v4, s40, v8
	v_rsq_f32_e32 v4, v4
	s_nop 0
	v_mov_b32_e32 v5, v4
	s_waitcnt vmcnt(8)
	v_pk_mul_f32 v[10:11], v[34:35], v[4:5]
	v_pk_mul_f32 v[10:11], v[10:11], v[130:131]
	v_pk_add_f32 v[12:13], v[196:197], v[6:7]
	v_pk_fma_f32 v[14:15], v[10:11], v[12:13], v[164:165]
	v_pk_mul_f32 v[10:11], v[36:37], v[4:5]
	v_pk_mul_f32 v[10:11], v[10:11], v[132:133]
	v_pk_add_f32 v[12:13], v[198:199], v[6:7]
	v_pk_fma_f32 v[16:17], v[10:11], v[12:13], v[166:167]
	v_cvt_pk_bf16_f32 v26, v14, v15
	v_cvt_pk_bf16_f32 v27, v16, v17
	global_store_dwordx2 v2, v[26:27], s[26:27]
	v_pk_mul_f32 v[10:11], v[38:39], v[4:5]
	v_pk_mul_f32 v[10:11], v[10:11], v[134:135]
	v_pk_add_f32 v[12:13], v[200:201], v[6:7]
	v_pk_fma_f32 v[14:15], v[10:11], v[12:13], v[168:169]
	v_pk_mul_f32 v[10:11], v[40:41], v[4:5]
	v_pk_mul_f32 v[10:11], v[10:11], v[136:137]
	v_pk_add_f32 v[12:13], v[202:203], v[6:7]
	v_pk_fma_f32 v[16:17], v[10:11], v[12:13], v[170:171]
	v_cvt_pk_bf16_f32 v28, v14, v15
	v_cvt_pk_bf16_f32 v29, v16, v17
	global_store_dwordx2 v2, v[28:29], s[26:27] offset:512
	v_pk_mul_f32 v[10:11], v[42:43], v[4:5]
	v_pk_mul_f32 v[10:11], v[10:11], v[138:139]
	v_pk_add_f32 v[12:13], v[204:205], v[6:7]
	v_pk_fma_f32 v[14:15], v[10:11], v[12:13], v[172:173]
	v_pk_mul_f32 v[10:11], v[44:45], v[4:5]
	v_pk_mul_f32 v[10:11], v[10:11], v[140:141]
	v_pk_add_f32 v[12:13], v[206:207], v[6:7]
	v_pk_fma_f32 v[16:17], v[10:11], v[12:13], v[174:175]
	v_cvt_pk_bf16_f32 v30, v14, v15
	v_cvt_pk_bf16_f32 v31, v16, v17
	global_store_dwordx2 v2, v[30:31], s[26:27] offset:1024
	v_pk_mul_f32 v[10:11], v[46:47], v[4:5]
	v_pk_mul_f32 v[10:11], v[10:11], v[142:143]
	v_pk_add_f32 v[12:13], v[208:209], v[6:7]
	v_pk_fma_f32 v[14:15], v[10:11], v[12:13], v[176:177]
	v_pk_mul_f32 v[10:11], v[48:49], v[4:5]
	v_pk_mul_f32 v[10:11], v[10:11], v[144:145]
	v_pk_add_f32 v[12:13], v[210:211], v[6:7]
	v_pk_fma_f32 v[16:17], v[10:11], v[12:13], v[178:179]
	v_cvt_pk_bf16_f32 v32, v14, v15
	v_cvt_pk_bf16_f32 v33, v16, v17
	global_store_dwordx2 v2, v[32:33], s[26:27] offset:1536
	v_pk_mul_f32 v[10:11], v[50:51], v[4:5]
	v_pk_mul_f32 v[10:11], v[10:11], v[146:147]
	v_pk_add_f32 v[12:13], v[212:213], v[6:7]
	v_pk_fma_f32 v[14:15], v[10:11], v[12:13], v[180:181]
	v_pk_mul_f32 v[10:11], v[52:53], v[4:5]
	v_pk_mul_f32 v[10:11], v[10:11], v[148:149]
	v_pk_add_f32 v[12:13], v[214:215], v[6:7]
	v_pk_fma_f32 v[16:17], v[10:11], v[12:13], v[182:183]
	v_cvt_pk_bf16_f32 v26, v14, v15
	v_cvt_pk_bf16_f32 v27, v16, v17
	global_store_dwordx2 v2, v[26:27], s[26:27] offset:2048
	v_pk_mul_f32 v[10:11], v[54:55], v[4:5]
	v_pk_mul_f32 v[10:11], v[10:11], v[150:151]
	v_pk_add_f32 v[12:13], v[216:217], v[6:7]
	v_pk_fma_f32 v[14:15], v[10:11], v[12:13], v[184:185]
	v_pk_mul_f32 v[10:11], v[56:57], v[4:5]
	v_pk_mul_f32 v[10:11], v[10:11], v[152:153]
	v_pk_add_f32 v[12:13], v[218:219], v[6:7]
	v_pk_fma_f32 v[16:17], v[10:11], v[12:13], v[186:187]
	v_cvt_pk_bf16_f32 v28, v14, v15
	v_cvt_pk_bf16_f32 v29, v16, v17
	global_store_dwordx2 v2, v[28:29], s[26:27] offset:2560
	v_pk_mul_f32 v[10:11], v[58:59], v[4:5]
	v_pk_mul_f32 v[10:11], v[10:11], v[156:157]
	v_pk_add_f32 v[12:13], v[220:221], v[6:7]
	v_pk_fma_f32 v[14:15], v[10:11], v[12:13], v[188:189]
	v_pk_mul_f32 v[10:11], v[60:61], v[4:5]
	v_pk_mul_f32 v[10:11], v[10:11], v[158:159]
	v_pk_add_f32 v[12:13], v[222:223], v[6:7]
	v_pk_fma_f32 v[16:17], v[10:11], v[12:13], v[190:191]
	v_cvt_pk_bf16_f32 v30, v14, v15
	v_cvt_pk_bf16_f32 v31, v16, v17
	global_store_dwordx2 v2, v[30:31], s[26:27] offset:3072
	v_pk_mul_f32 v[10:11], v[62:63], v[4:5]
	v_pk_mul_f32 v[10:11], v[10:11], v[160:161]
	v_pk_add_f32 v[12:13], v[224:225], v[6:7]
	v_pk_fma_f32 v[14:15], v[10:11], v[12:13], v[192:193]
	v_pk_mul_f32 v[10:11], v[64:65], v[4:5]
	v_pk_mul_f32 v[10:11], v[10:11], v[162:163]
	v_pk_add_f32 v[12:13], v[226:227], v[6:7]
	v_pk_fma_f32 v[16:17], v[10:11], v[12:13], v[194:195]
	v_cvt_pk_bf16_f32 v32, v14, v15
	v_cvt_pk_bf16_f32 v33, v16, v17
	global_store_dwordx2 v2, v[32:33], s[26:27] offset:3584
	s_mov_b32 s16, 4
	s_add_u32 s17, s16, 0
	s_mul_i32 s17, s17, 49152
	s_add_u32 s17, s17, 0x10404000
	s_add_u32 s28, s90, s17
	s_addc_u32 s29, s91, 0
	s_add_u32 s17, s16, 0
	s_mul_i32 s17, s17, 49152
	s_add_u32 s17, s17, 0x10400000
	s_add_u32 s30, s90, s17
	s_addc_u32 s31, s91, 0
	s_add_u32 s32, s30, 0x2000
	s_addc_u32 s33, s31, 0
	s_add_u32 s18, s2, 0x1000
	s_addc_u32 s19, s3, 0
	global_load_dwordx4 v[130:133], v1, s[2:3]
	global_load_dwordx4 v[134:137], v1, s[2:3] offset:1024
	global_load_dwordx4 v[138:141], v1, s[2:3] offset:2048
	global_load_dwordx4 v[142:145], v1, s[2:3] offset:3072
	global_load_dwordx4 v[146:149], v1, s[18:19]
	global_load_dwordx4 v[150:153], v1, s[18:19] offset:1024
	global_load_dwordx4 v[156:159], v1, s[18:19] offset:2048
	global_load_dwordx4 v[160:163], v1, s[18:19] offset:3072
	s_add_u32 s18, s30, 0x1000
	s_addc_u32 s19, s31, 0
	global_load_dwordx4 v[164:167], v1, s[30:31]
	global_load_dwordx4 v[168:171], v1, s[30:31] offset:1024
	global_load_dwordx4 v[172:175], v1, s[30:31] offset:2048
	global_load_dwordx4 v[176:179], v1, s[30:31] offset:3072
	global_load_dwordx4 v[180:183], v1, s[18:19]
	global_load_dwordx4 v[184:187], v1, s[18:19] offset:1024
	global_load_dwordx4 v[188:191], v1, s[18:19] offset:2048
	global_load_dwordx4 v[192:195], v1, s[18:19] offset:3072
	s_add_u32 s18, s32, 0x1000
	s_addc_u32 s19, s33, 0
	global_load_dwordx4 v[196:199], v1, s[32:33]
	global_load_dwordx4 v[200:203], v1, s[32:33] offset:1024
	global_load_dwordx4 v[204:207], v1, s[32:33] offset:2048
	global_load_dwordx4 v[208:211], v1, s[32:33] offset:3072
	global_load_dwordx4 v[212:215], v1, s[18:19]
	global_load_dwordx4 v[216:219], v1, s[18:19] offset:1024
	global_load_dwordx4 v[220:223], v1, s[18:19] offset:2048
	global_load_dwordx4 v[224:227], v1, s[18:19] offset:3072
	s_add_u32 s12, s10, 4096
	s_lshl_b32 s13, s12, 13
	s_lshl_b32 s14, s12, 12
	s_sub_u32 s15, s13, 0x2000000
	s_add_u32 s20, s8, s15
	s_addc_u32 s21, s9, 0
	s_add_u32 s22, s90, 0x21918000
	s_addc_u32 s23, s91, 0
	s_add_u32 s22, s22, s14
	s_addc_u32 s23, s23, 0
	s_add_u32 s36, s20, 0x1000
	s_addc_u32 s37, s21, 0
	global_load_dwordx4 v[34:37], v1, s[20:21] nt
	global_load_dwordx4 v[38:41], v1, s[20:21] offset:1024 nt
	global_load_dwordx4 v[42:45], v1, s[20:21] offset:2048 nt
	global_load_dwordx4 v[46:49], v1, s[20:21] offset:3072 nt
	global_load_dwordx4 v[50:53], v1, s[36:37] nt
	global_load_dwordx4 v[54:57], v1, s[36:37] offset:1024 nt
	global_load_dwordx4 v[58:61], v1, s[36:37] offset:2048 nt
	global_load_dwordx4 v[62:65], v1, s[36:37] offset:3072 nt
	s_add_u32 s12, s10, 2048
	s_lshl_b32 s14, s12, 12
	s_add_u32 s26, s90, 0x11918000
	s_addc_u32 s27, s91, 0
	s_add_u32 s26, s26, s14
	s_addc_u32 s27, s27, 0
	s_waitcnt vmcnt(40)
	v_mov_b32_e32 v8, 0
	v_fmac_f32_e32 v8, v66, v66
	v_fmac_f32_e32 v8, v67, v67
	v_fmac_f32_e32 v8, v68, v68
	v_fmac_f32_e32 v8, v69, v69
	v_fmac_f32_e32 v8, v70, v70
	v_fmac_f32_e32 v8, v71, v71
	v_fmac_f32_e32 v8, v72, v72
	v_fmac_f32_e32 v8, v73, v73
	v_fmac_f32_e32 v8, v74, v74
	v_fmac_f32_e32 v8, v75, v75
	v_fmac_f32_e32 v8, v76, v76
	v_fmac_f32_e32 v8, v77, v77
	v_fmac_f32_e32 v8, v78, v78
	v_fmac_f32_e32 v8, v79, v79
	v_fmac_f32_e32 v8, v80, v80
	v_fmac_f32_e32 v8, v81, v81
	v_fmac_f32_e32 v8, v82, v82
	v_fmac_f32_e32 v8, v83, v83
	v_fmac_f32_e32 v8, v84, v84
	v_fmac_f32_e32 v8, v85, v85
	v_fmac_f32_e32 v8, v86, v86
	v_fmac_f32_e32 v8, v87, v87
	v_fmac_f32_e32 v8, v88, v88
	v_fmac_f32_e32 v8, v89, v89
	v_fmac_f32_e32 v8, v90, v90
	v_fmac_f32_e32 v8, v91, v91
	v_fmac_f32_e32 v8, v92, v92
	v_fmac_f32_e32 v8, v93, v93
	v_fmac_f32_e32 v8, v94, v94
	v_fmac_f32_e32 v8, v95, v95
	v_fmac_f32_e32 v8, v96, v96
	v_fmac_f32_e32 v8, v97, v97
	s_nop 1
	v_add_f32_dpp v8, v8, v8 quad_perm:[1,0,3,2] row_mask:0xf bank_mask:0xf
	s_nop 1
	v_add_f32_dpp v8, v8, v8 quad_perm:[2,3,0,1] row_mask:0xf bank_mask:0xf
	s_nop 1
	v_add_f32_dpp v8, v8, v8 row_ror:4 row_mask:0xf bank_mask:0xf
	s_nop 1
	v_add_f32_dpp v8, v8, v8 row_ror:8 row_mask:0xf bank_mask:0xf
	s_nop 1
	v_readlane_b32 s42, v8, 0
	v_readlane_b32 s43, v8, 16
	v_readlane_b32 s44, v8, 32
	v_readlane_b32 s45, v8, 48
	s_nop 1
	v_mov_b32_e32 v8, s42
	v_add_f32_e32 v8, s43, v8
	v_add_f32_e32 v8, s44, v8
	v_add_f32_e32 v8, s45, v8
	v_mov_b32_e32 v4, s41
	v_fmac_f32_e32 v4, s40, v8
	v_rsq_f32_e32 v4, v4
	s_nop 0
	v_mov_b32_e32 v5, v4
	s_waitcnt vmcnt(8)
	v_pk_mul_f32 v[10:11], v[66:67], v[4:5]
	v_pk_mul_f32 v[10:11], v[10:11], v[130:131]
	v_pk_add_f32 v[12:13], v[196:197], v[6:7]
	v_pk_fma_f32 v[14:15], v[10:11], v[12:13], v[164:165]
	v_pk_mul_f32 v[10:11], v[68:69], v[4:5]
	v_pk_mul_f32 v[10:11], v[10:11], v[132:133]
	v_pk_add_f32 v[12:13], v[198:199], v[6:7]
	v_pk_fma_f32 v[16:17], v[10:11], v[12:13], v[166:167]
	v_cvt_pk_bf16_f32 v26, v14, v15
	v_cvt_pk_bf16_f32 v27, v16, v17
	global_store_dwordx2 v2, v[26:27], s[26:27]
	v_pk_mul_f32 v[10:11], v[70:71], v[4:5]
	v_pk_mul_f32 v[10:11], v[10:11], v[134:135]
	v_pk_add_f32 v[12:13], v[200:201], v[6:7]
	v_pk_fma_f32 v[14:15], v[10:11], v[12:13], v[168:169]
	v_pk_mul_f32 v[10:11], v[72:73], v[4:5]
	v_pk_mul_f32 v[10:11], v[10:11], v[136:137]
	v_pk_add_f32 v[12:13], v[202:203], v[6:7]
	v_pk_fma_f32 v[16:17], v[10:11], v[12:13], v[170:171]
	v_cvt_pk_bf16_f32 v28, v14, v15
	v_cvt_pk_bf16_f32 v29, v16, v17
	global_store_dwordx2 v2, v[28:29], s[26:27] offset:512
	v_pk_mul_f32 v[10:11], v[74:75], v[4:5]
	v_pk_mul_f32 v[10:11], v[10:11], v[138:139]
	v_pk_add_f32 v[12:13], v[204:205], v[6:7]
	v_pk_fma_f32 v[14:15], v[10:11], v[12:13], v[172:173]
	v_pk_mul_f32 v[10:11], v[76:77], v[4:5]
	v_pk_mul_f32 v[10:11], v[10:11], v[140:141]
	v_pk_add_f32 v[12:13], v[206:207], v[6:7]
	v_pk_fma_f32 v[16:17], v[10:11], v[12:13], v[174:175]
	v_cvt_pk_bf16_f32 v30, v14, v15
	v_cvt_pk_bf16_f32 v31, v16, v17
	global_store_dwordx2 v2, v[30:31], s[26:27] offset:1024
	v_pk_mul_f32 v[10:11], v[78:79], v[4:5]
	v_pk_mul_f32 v[10:11], v[10:11], v[142:143]
	v_pk_add_f32 v[12:13], v[208:209], v[6:7]
	v_pk_fma_f32 v[14:15], v[10:11], v[12:13], v[176:177]
	v_pk_mul_f32 v[10:11], v[80:81], v[4:5]
	v_pk_mul_f32 v[10:11], v[10:11], v[144:145]
	v_pk_add_f32 v[12:13], v[210:211], v[6:7]
	v_pk_fma_f32 v[16:17], v[10:11], v[12:13], v[178:179]
	v_cvt_pk_bf16_f32 v32, v14, v15
	v_cvt_pk_bf16_f32 v33, v16, v17
	global_store_dwordx2 v2, v[32:33], s[26:27] offset:1536
	v_pk_mul_f32 v[10:11], v[82:83], v[4:5]
	v_pk_mul_f32 v[10:11], v[10:11], v[146:147]
	v_pk_add_f32 v[12:13], v[212:213], v[6:7]
	v_pk_fma_f32 v[14:15], v[10:11], v[12:13], v[180:181]
	v_pk_mul_f32 v[10:11], v[84:85], v[4:5]
	v_pk_mul_f32 v[10:11], v[10:11], v[148:149]
	v_pk_add_f32 v[12:13], v[214:215], v[6:7]
	v_pk_fma_f32 v[16:17], v[10:11], v[12:13], v[182:183]
	v_cvt_pk_bf16_f32 v26, v14, v15
	v_cvt_pk_bf16_f32 v27, v16, v17
	global_store_dwordx2 v2, v[26:27], s[26:27] offset:2048
	v_pk_mul_f32 v[10:11], v[86:87], v[4:5]
	v_pk_mul_f32 v[10:11], v[10:11], v[150:151]
	v_pk_add_f32 v[12:13], v[216:217], v[6:7]
	v_pk_fma_f32 v[14:15], v[10:11], v[12:13], v[184:185]
	v_pk_mul_f32 v[10:11], v[88:89], v[4:5]
	v_pk_mul_f32 v[10:11], v[10:11], v[152:153]
	v_pk_add_f32 v[12:13], v[218:219], v[6:7]
	v_pk_fma_f32 v[16:17], v[10:11], v[12:13], v[186:187]
	v_cvt_pk_bf16_f32 v28, v14, v15
	v_cvt_pk_bf16_f32 v29, v16, v17
	global_store_dwordx2 v2, v[28:29], s[26:27] offset:2560
	v_pk_mul_f32 v[10:11], v[90:91], v[4:5]
	v_pk_mul_f32 v[10:11], v[10:11], v[156:157]
	v_pk_add_f32 v[12:13], v[220:221], v[6:7]
	v_pk_fma_f32 v[14:15], v[10:11], v[12:13], v[188:189]
	v_pk_mul_f32 v[10:11], v[92:93], v[4:5]
	v_pk_mul_f32 v[10:11], v[10:11], v[158:159]
	v_pk_add_f32 v[12:13], v[222:223], v[6:7]
	v_pk_fma_f32 v[16:17], v[10:11], v[12:13], v[190:191]
	v_cvt_pk_bf16_f32 v30, v14, v15
	v_cvt_pk_bf16_f32 v31, v16, v17
	global_store_dwordx2 v2, v[30:31], s[26:27] offset:3072
	v_pk_mul_f32 v[10:11], v[94:95], v[4:5]
	v_pk_mul_f32 v[10:11], v[10:11], v[160:161]
	v_pk_add_f32 v[12:13], v[224:225], v[6:7]
	v_pk_fma_f32 v[14:15], v[10:11], v[12:13], v[192:193]
	v_pk_mul_f32 v[10:11], v[96:97], v[4:5]
	v_pk_mul_f32 v[10:11], v[10:11], v[162:163]
	v_pk_add_f32 v[12:13], v[226:227], v[6:7]
	v_pk_fma_f32 v[16:17], v[10:11], v[12:13], v[194:195]
	v_cvt_pk_bf16_f32 v32, v14, v15
	v_cvt_pk_bf16_f32 v33, v16, v17
	global_store_dwordx2 v2, v[32:33], s[26:27] offset:3584
	s_lshr_b32 s16, s10, 10
	s_add_u32 s17, s16, 0
	s_mul_i32 s17, s17, 49152
	s_add_u32 s17, s17, 0x10404000
	s_add_u32 s28, s90, s17
	s_addc_u32 s29, s91, 0
	s_add_u32 s17, s16, 0
	s_mul_i32 s17, s17, 49152
	s_add_u32 s17, s17, 0x10400000
	s_add_u32 s30, s90, s17
	s_addc_u32 s31, s91, 0
	s_add_u32 s32, s30, 0x2000
	s_addc_u32 s33, s31, 0
	s_add_u32 s18, s2, 0x1000
	s_addc_u32 s19, s3, 0
	global_load_dwordx4 v[130:133], v1, s[2:3]
	global_load_dwordx4 v[134:137], v1, s[2:3] offset:1024
	global_load_dwordx4 v[138:141], v1, s[2:3] offset:2048
	global_load_dwordx4 v[142:145], v1, s[2:3] offset:3072
	global_load_dwordx4 v[146:149], v1, s[18:19]
	global_load_dwordx4 v[150:153], v1, s[18:19] offset:1024
	global_load_dwordx4 v[156:159], v1, s[18:19] offset:2048
	global_load_dwordx4 v[160:163], v1, s[18:19] offset:3072
	s_add_u32 s18, s30, 0x1000
	s_addc_u32 s19, s31, 0
	global_load_dwordx4 v[164:167], v1, s[30:31]
	global_load_dwordx4 v[168:171], v1, s[30:31] offset:1024
	global_load_dwordx4 v[172:175], v1, s[30:31] offset:2048
	global_load_dwordx4 v[176:179], v1, s[30:31] offset:3072
	global_load_dwordx4 v[180:183], v1, s[18:19]
	global_load_dwordx4 v[184:187], v1, s[18:19] offset:1024
	global_load_dwordx4 v[188:191], v1, s[18:19] offset:2048
	global_load_dwordx4 v[192:195], v1, s[18:19] offset:3072
	s_add_u32 s18, s32, 0x1000
	s_addc_u32 s19, s33, 0
	global_load_dwordx4 v[196:199], v1, s[32:33]
	global_load_dwordx4 v[200:203], v1, s[32:33] offset:1024
	global_load_dwordx4 v[204:207], v1, s[32:33] offset:2048
	global_load_dwordx4 v[208:211], v1, s[32:33] offset:3072
	global_load_dwordx4 v[212:215], v1, s[18:19]
	global_load_dwordx4 v[216:219], v1, s[18:19] offset:1024
	global_load_dwordx4 v[220:223], v1, s[18:19] offset:2048
	global_load_dwordx4 v[224:227], v1, s[18:19] offset:3072
	s_add_u32 s12, s10, 6144
	s_lshl_b32 s13, s12, 13
	s_lshl_b32 s14, s12, 12
	s_sub_u32 s15, s13, 0x2000000
	s_add_u32 s20, s8, s15
	s_addc_u32 s21, s9, 0
	s_add_u32 s22, s90, 0x21918000
	s_addc_u32 s23, s91, 0
	s_add_u32 s22, s22, s14
	s_addc_u32 s23, s23, 0
	s_add_u32 s36, s20, 0x1000
	s_addc_u32 s37, s21, 0
	global_load_dwordx4 v[66:69], v1, s[20:21] nt
	global_load_dwordx4 v[70:73], v1, s[20:21] offset:1024 nt
	global_load_dwordx4 v[74:77], v1, s[20:21] offset:2048 nt
	global_load_dwordx4 v[78:81], v1, s[20:21] offset:3072 nt
	global_load_dwordx4 v[82:85], v1, s[36:37] nt
	global_load_dwordx4 v[86:89], v1, s[36:37] offset:1024 nt
	global_load_dwordx4 v[90:93], v1, s[36:37] offset:2048 nt
	global_load_dwordx4 v[94:97], v1, s[36:37] offset:3072 nt
	s_add_u32 s12, s10, 4096
	s_lshl_b32 s14, s12, 12
	s_add_u32 s26, s90, 0x11918000
	s_addc_u32 s27, s91, 0
	s_add_u32 s26, s26, s14
	s_addc_u32 s27, s27, 0
	s_waitcnt vmcnt(40)
	v_mov_b32_e32 v8, 0
	v_fmac_f32_e32 v8, v34, v34
	v_fmac_f32_e32 v8, v35, v35
	v_fmac_f32_e32 v8, v36, v36
	v_fmac_f32_e32 v8, v37, v37
	v_fmac_f32_e32 v8, v38, v38
	v_fmac_f32_e32 v8, v39, v39
	v_fmac_f32_e32 v8, v40, v40
	v_fmac_f32_e32 v8, v41, v41
	v_fmac_f32_e32 v8, v42, v42
	v_fmac_f32_e32 v8, v43, v43
	v_fmac_f32_e32 v8, v44, v44
	v_fmac_f32_e32 v8, v45, v45
	v_fmac_f32_e32 v8, v46, v46
	v_fmac_f32_e32 v8, v47, v47
	v_fmac_f32_e32 v8, v48, v48
	v_fmac_f32_e32 v8, v49, v49
	v_fmac_f32_e32 v8, v50, v50
	v_fmac_f32_e32 v8, v51, v51
	v_fmac_f32_e32 v8, v52, v52
	v_fmac_f32_e32 v8, v53, v53
	v_fmac_f32_e32 v8, v54, v54
	v_fmac_f32_e32 v8, v55, v55
	v_fmac_f32_e32 v8, v56, v56
	v_fmac_f32_e32 v8, v57, v57
	v_fmac_f32_e32 v8, v58, v58
	v_fmac_f32_e32 v8, v59, v59
	v_fmac_f32_e32 v8, v60, v60
	v_fmac_f32_e32 v8, v61, v61
	v_fmac_f32_e32 v8, v62, v62
	v_fmac_f32_e32 v8, v63, v63
	v_fmac_f32_e32 v8, v64, v64
	v_fmac_f32_e32 v8, v65, v65
	s_nop 1
	v_add_f32_dpp v8, v8, v8 quad_perm:[1,0,3,2] row_mask:0xf bank_mask:0xf
	s_nop 1
	v_add_f32_dpp v8, v8, v8 quad_perm:[2,3,0,1] row_mask:0xf bank_mask:0xf
	s_nop 1
	v_add_f32_dpp v8, v8, v8 row_ror:4 row_mask:0xf bank_mask:0xf
	s_nop 1
	v_add_f32_dpp v8, v8, v8 row_ror:8 row_mask:0xf bank_mask:0xf
	s_nop 1
	v_readlane_b32 s42, v8, 0
	v_readlane_b32 s43, v8, 16
	v_readlane_b32 s44, v8, 32
	v_readlane_b32 s45, v8, 48
	s_nop 1
	v_mov_b32_e32 v8, s42
	v_add_f32_e32 v8, s43, v8
	v_add_f32_e32 v8, s44, v8
	v_add_f32_e32 v8, s45, v8
	v_mov_b32_e32 v4, s41
	v_fmac_f32_e32 v4, s40, v8
	v_rsq_f32_e32 v4, v4
	s_nop 0
	v_mov_b32_e32 v5, v4
	s_waitcnt vmcnt(8)
	v_pk_mul_f32 v[10:11], v[34:35], v[4:5]
	v_pk_mul_f32 v[10:11], v[10:11], v[130:131]
	v_pk_add_f32 v[12:13], v[196:197], v[6:7]
	v_pk_fma_f32 v[14:15], v[10:11], v[12:13], v[164:165]
	v_pk_mul_f32 v[10:11], v[36:37], v[4:5]
	v_pk_mul_f32 v[10:11], v[10:11], v[132:133]
	v_pk_add_f32 v[12:13], v[198:199], v[6:7]
	v_pk_fma_f32 v[16:17], v[10:11], v[12:13], v[166:167]
	v_cvt_pk_bf16_f32 v26, v14, v15
	v_cvt_pk_bf16_f32 v27, v16, v17
	global_store_dwordx2 v2, v[26:27], s[26:27]
	v_pk_mul_f32 v[10:11], v[38:39], v[4:5]
	v_pk_mul_f32 v[10:11], v[10:11], v[134:135]
	v_pk_add_f32 v[12:13], v[200:201], v[6:7]
	v_pk_fma_f32 v[14:15], v[10:11], v[12:13], v[168:169]
	v_pk_mul_f32 v[10:11], v[40:41], v[4:5]
	v_pk_mul_f32 v[10:11], v[10:11], v[136:137]
	v_pk_add_f32 v[12:13], v[202:203], v[6:7]
	v_pk_fma_f32 v[16:17], v[10:11], v[12:13], v[170:171]
	v_cvt_pk_bf16_f32 v28, v14, v15
	v_cvt_pk_bf16_f32 v29, v16, v17
	global_store_dwordx2 v2, v[28:29], s[26:27] offset:512
	v_pk_mul_f32 v[10:11], v[42:43], v[4:5]
	v_pk_mul_f32 v[10:11], v[10:11], v[138:139]
	v_pk_add_f32 v[12:13], v[204:205], v[6:7]
	v_pk_fma_f32 v[14:15], v[10:11], v[12:13], v[172:173]
	v_pk_mul_f32 v[10:11], v[44:45], v[4:5]
	v_pk_mul_f32 v[10:11], v[10:11], v[140:141]
	v_pk_add_f32 v[12:13], v[206:207], v[6:7]
	v_pk_fma_f32 v[16:17], v[10:11], v[12:13], v[174:175]
	v_cvt_pk_bf16_f32 v30, v14, v15
	v_cvt_pk_bf16_f32 v31, v16, v17
	global_store_dwordx2 v2, v[30:31], s[26:27] offset:1024
	v_pk_mul_f32 v[10:11], v[46:47], v[4:5]
	v_pk_mul_f32 v[10:11], v[10:11], v[142:143]
	v_pk_add_f32 v[12:13], v[208:209], v[6:7]
	v_pk_fma_f32 v[14:15], v[10:11], v[12:13], v[176:177]
	v_pk_mul_f32 v[10:11], v[48:49], v[4:5]
	v_pk_mul_f32 v[10:11], v[10:11], v[144:145]
	v_pk_add_f32 v[12:13], v[210:211], v[6:7]
	v_pk_fma_f32 v[16:17], v[10:11], v[12:13], v[178:179]
	v_cvt_pk_bf16_f32 v32, v14, v15
	v_cvt_pk_bf16_f32 v33, v16, v17
	global_store_dwordx2 v2, v[32:33], s[26:27] offset:1536
	v_pk_mul_f32 v[10:11], v[50:51], v[4:5]
	v_pk_mul_f32 v[10:11], v[10:11], v[146:147]
	v_pk_add_f32 v[12:13], v[212:213], v[6:7]
	v_pk_fma_f32 v[14:15], v[10:11], v[12:13], v[180:181]
	v_pk_mul_f32 v[10:11], v[52:53], v[4:5]
	v_pk_mul_f32 v[10:11], v[10:11], v[148:149]
	v_pk_add_f32 v[12:13], v[214:215], v[6:7]
	v_pk_fma_f32 v[16:17], v[10:11], v[12:13], v[182:183]
	v_cvt_pk_bf16_f32 v26, v14, v15
	v_cvt_pk_bf16_f32 v27, v16, v17
	global_store_dwordx2 v2, v[26:27], s[26:27] offset:2048
	v_pk_mul_f32 v[10:11], v[54:55], v[4:5]
	v_pk_mul_f32 v[10:11], v[10:11], v[150:151]
	v_pk_add_f32 v[12:13], v[216:217], v[6:7]
	v_pk_fma_f32 v[14:15], v[10:11], v[12:13], v[184:185]
	v_pk_mul_f32 v[10:11], v[56:57], v[4:5]
	v_pk_mul_f32 v[10:11], v[10:11], v[152:153]
	v_pk_add_f32 v[12:13], v[218:219], v[6:7]
	v_pk_fma_f32 v[16:17], v[10:11], v[12:13], v[186:187]
	v_cvt_pk_bf16_f32 v28, v14, v15
	v_cvt_pk_bf16_f32 v29, v16, v17
	global_store_dwordx2 v2, v[28:29], s[26:27] offset:2560
	v_pk_mul_f32 v[10:11], v[58:59], v[4:5]
	v_pk_mul_f32 v[10:11], v[10:11], v[156:157]
	v_pk_add_f32 v[12:13], v[220:221], v[6:7]
	v_pk_fma_f32 v[14:15], v[10:11], v[12:13], v[188:189]
	v_pk_mul_f32 v[10:11], v[60:61], v[4:5]
	v_pk_mul_f32 v[10:11], v[10:11], v[158:159]
	v_pk_add_f32 v[12:13], v[222:223], v[6:7]
	v_pk_fma_f32 v[16:17], v[10:11], v[12:13], v[190:191]
	v_cvt_pk_bf16_f32 v30, v14, v15
	v_cvt_pk_bf16_f32 v31, v16, v17
	global_store_dwordx2 v2, v[30:31], s[26:27] offset:3072
	v_pk_mul_f32 v[10:11], v[62:63], v[4:5]
	v_pk_mul_f32 v[10:11], v[10:11], v[160:161]
	v_pk_add_f32 v[12:13], v[224:225], v[6:7]
	v_pk_fma_f32 v[14:15], v[10:11], v[12:13], v[192:193]
	v_pk_mul_f32 v[10:11], v[64:65], v[4:5]
	v_pk_mul_f32 v[10:11], v[10:11], v[162:163]
	v_pk_add_f32 v[12:13], v[226:227], v[6:7]
	v_pk_fma_f32 v[16:17], v[10:11], v[12:13], v[194:195]
	v_cvt_pk_bf16_f32 v32, v14, v15
	v_cvt_pk_bf16_f32 v33, v16, v17
	global_store_dwordx2 v2, v[32:33], s[26:27] offset:3584
	s_lshr_b32 s16, s10, 10
	s_add_u32 s16, s16, 2
	s_add_u32 s17, s16, 0
	s_mul_i32 s17, s17, 49152
	s_add_u32 s17, s17, 0x10404000
	s_add_u32 s28, s90, s17
	s_addc_u32 s29, s91, 0
	s_add_u32 s17, s16, 0
	s_mul_i32 s17, s17, 49152
	s_add_u32 s17, s17, 0x10400000
	s_add_u32 s30, s90, s17
	s_addc_u32 s31, s91, 0
	s_add_u32 s32, s30, 0x2000
	s_addc_u32 s33, s31, 0
	s_add_u32 s18, s2, 0x1000
	s_addc_u32 s19, s3, 0
	global_load_dwordx4 v[130:133], v1, s[2:3]
	global_load_dwordx4 v[134:137], v1, s[2:3] offset:1024
	global_load_dwordx4 v[138:141], v1, s[2:3] offset:2048
	global_load_dwordx4 v[142:145], v1, s[2:3] offset:3072
	global_load_dwordx4 v[146:149], v1, s[18:19]
	global_load_dwordx4 v[150:153], v1, s[18:19] offset:1024
	global_load_dwordx4 v[156:159], v1, s[18:19] offset:2048
	global_load_dwordx4 v[160:163], v1, s[18:19] offset:3072
	s_add_u32 s18, s30, 0x1000
	s_addc_u32 s19, s31, 0
	global_load_dwordx4 v[164:167], v1, s[30:31]
	global_load_dwordx4 v[168:171], v1, s[30:31] offset:1024
	global_load_dwordx4 v[172:175], v1, s[30:31] offset:2048
	global_load_dwordx4 v[176:179], v1, s[30:31] offset:3072
	global_load_dwordx4 v[180:183], v1, s[18:19]
	global_load_dwordx4 v[184:187], v1, s[18:19] offset:1024
	global_load_dwordx4 v[188:191], v1, s[18:19] offset:2048
	global_load_dwordx4 v[192:195], v1, s[18:19] offset:3072
	s_add_u32 s18, s32, 0x1000
	s_addc_u32 s19, s33, 0
	global_load_dwordx4 v[196:199], v1, s[32:33]
	global_load_dwordx4 v[200:203], v1, s[32:33] offset:1024
	global_load_dwordx4 v[204:207], v1, s[32:33] offset:2048
	global_load_dwordx4 v[208:211], v1, s[32:33] offset:3072
	global_load_dwordx4 v[212:215], v1, s[18:19]
	global_load_dwordx4 v[216:219], v1, s[18:19] offset:1024
	global_load_dwordx4 v[220:223], v1, s[18:19] offset:2048
	global_load_dwordx4 v[224:227], v1, s[18:19] offset:3072
	s_add_u32 s12, s10, 6144
	s_lshl_b32 s14, s12, 12
	s_add_u32 s26, s90, 0x11918000
	s_addc_u32 s27, s91, 0
	s_add_u32 s26, s26, s14
	s_addc_u32 s27, s27, 0
	s_waitcnt vmcnt(32)
	v_mov_b32_e32 v8, 0
	v_fmac_f32_e32 v8, v66, v66
	v_fmac_f32_e32 v8, v67, v67
	v_fmac_f32_e32 v8, v68, v68
	v_fmac_f32_e32 v8, v69, v69
	v_fmac_f32_e32 v8, v70, v70
	v_fmac_f32_e32 v8, v71, v71
	v_fmac_f32_e32 v8, v72, v72
	v_fmac_f32_e32 v8, v73, v73
	v_fmac_f32_e32 v8, v74, v74
	v_fmac_f32_e32 v8, v75, v75
	v_fmac_f32_e32 v8, v76, v76
	v_fmac_f32_e32 v8, v77, v77
	v_fmac_f32_e32 v8, v78, v78
	v_fmac_f32_e32 v8, v79, v79
	v_fmac_f32_e32 v8, v80, v80
	v_fmac_f32_e32 v8, v81, v81
	v_fmac_f32_e32 v8, v82, v82
	v_fmac_f32_e32 v8, v83, v83
	v_fmac_f32_e32 v8, v84, v84
	v_fmac_f32_e32 v8, v85, v85
	v_fmac_f32_e32 v8, v86, v86
	v_fmac_f32_e32 v8, v87, v87
	v_fmac_f32_e32 v8, v88, v88
	v_fmac_f32_e32 v8, v89, v89
	v_fmac_f32_e32 v8, v90, v90
	v_fmac_f32_e32 v8, v91, v91
	v_fmac_f32_e32 v8, v92, v92
	v_fmac_f32_e32 v8, v93, v93
	v_fmac_f32_e32 v8, v94, v94
	v_fmac_f32_e32 v8, v95, v95
	v_fmac_f32_e32 v8, v96, v96
	v_fmac_f32_e32 v8, v97, v97
	s_nop 1
	v_add_f32_dpp v8, v8, v8 quad_perm:[1,0,3,2] row_mask:0xf bank_mask:0xf
	s_nop 1
	v_add_f32_dpp v8, v8, v8 quad_perm:[2,3,0,1] row_mask:0xf bank_mask:0xf
	s_nop 1
	v_add_f32_dpp v8, v8, v8 row_ror:4 row_mask:0xf bank_mask:0xf
	s_nop 1
	v_add_f32_dpp v8, v8, v8 row_ror:8 row_mask:0xf bank_mask:0xf
	s_nop 1
	v_readlane_b32 s42, v8, 0
	v_readlane_b32 s43, v8, 16
	v_readlane_b32 s44, v8, 32
	v_readlane_b32 s45, v8, 48
	s_nop 1
	v_mov_b32_e32 v8, s42
	v_add_f32_e32 v8, s43, v8
	v_add_f32_e32 v8, s44, v8
	v_add_f32_e32 v8, s45, v8
	v_mov_b32_e32 v4, s41
	v_fmac_f32_e32 v4, s40, v8
	v_rsq_f32_e32 v4, v4
	s_nop 0
	v_mov_b32_e32 v5, v4
	s_waitcnt vmcnt(0)
	v_pk_mul_f32 v[10:11], v[66:67], v[4:5]
	v_pk_mul_f32 v[10:11], v[10:11], v[130:131]
	v_pk_add_f32 v[12:13], v[196:197], v[6:7]
	v_pk_fma_f32 v[14:15], v[10:11], v[12:13], v[164:165]
	v_pk_mul_f32 v[10:11], v[68:69], v[4:5]
	v_pk_mul_f32 v[10:11], v[10:11], v[132:133]
	v_pk_add_f32 v[12:13], v[198:199], v[6:7]
	v_pk_fma_f32 v[16:17], v[10:11], v[12:13], v[166:167]
	v_cvt_pk_bf16_f32 v26, v14, v15
	v_cvt_pk_bf16_f32 v27, v16, v17
	global_store_dwordx2 v2, v[26:27], s[26:27]
	v_pk_mul_f32 v[10:11], v[70:71], v[4:5]
	v_pk_mul_f32 v[10:11], v[10:11], v[134:135]
	v_pk_add_f32 v[12:13], v[200:201], v[6:7]
	v_pk_fma_f32 v[14:15], v[10:11], v[12:13], v[168:169]
	v_pk_mul_f32 v[10:11], v[72:73], v[4:5]
	v_pk_mul_f32 v[10:11], v[10:11], v[136:137]
	v_pk_add_f32 v[12:13], v[202:203], v[6:7]
	v_pk_fma_f32 v[16:17], v[10:11], v[12:13], v[170:171]
	v_cvt_pk_bf16_f32 v28, v14, v15
	v_cvt_pk_bf16_f32 v29, v16, v17
	global_store_dwordx2 v2, v[28:29], s[26:27] offset:512
	v_pk_mul_f32 v[10:11], v[74:75], v[4:5]
	v_pk_mul_f32 v[10:11], v[10:11], v[138:139]
	v_pk_add_f32 v[12:13], v[204:205], v[6:7]
	v_pk_fma_f32 v[14:15], v[10:11], v[12:13], v[172:173]
	v_pk_mul_f32 v[10:11], v[76:77], v[4:5]
	v_pk_mul_f32 v[10:11], v[10:11], v[140:141]
	v_pk_add_f32 v[12:13], v[206:207], v[6:7]
	v_pk_fma_f32 v[16:17], v[10:11], v[12:13], v[174:175]
	v_cvt_pk_bf16_f32 v30, v14, v15
	v_cvt_pk_bf16_f32 v31, v16, v17
	global_store_dwordx2 v2, v[30:31], s[26:27] offset:1024
	v_pk_mul_f32 v[10:11], v[78:79], v[4:5]
	v_pk_mul_f32 v[10:11], v[10:11], v[142:143]
	v_pk_add_f32 v[12:13], v[208:209], v[6:7]
	v_pk_fma_f32 v[14:15], v[10:11], v[12:13], v[176:177]
	v_pk_mul_f32 v[10:11], v[80:81], v[4:5]
	v_pk_mul_f32 v[10:11], v[10:11], v[144:145]
	v_pk_add_f32 v[12:13], v[210:211], v[6:7]
	v_pk_fma_f32 v[16:17], v[10:11], v[12:13], v[178:179]
	v_cvt_pk_bf16_f32 v32, v14, v15
	v_cvt_pk_bf16_f32 v33, v16, v17
	global_store_dwordx2 v2, v[32:33], s[26:27] offset:1536
	v_pk_mul_f32 v[10:11], v[82:83], v[4:5]
	v_pk_mul_f32 v[10:11], v[10:11], v[146:147]
	v_pk_add_f32 v[12:13], v[212:213], v[6:7]
	v_pk_fma_f32 v[14:15], v[10:11], v[12:13], v[180:181]
	v_pk_mul_f32 v[10:11], v[84:85], v[4:5]
	v_pk_mul_f32 v[10:11], v[10:11], v[148:149]
	v_pk_add_f32 v[12:13], v[214:215], v[6:7]
	v_pk_fma_f32 v[16:17], v[10:11], v[12:13], v[182:183]
	v_cvt_pk_bf16_f32 v26, v14, v15
	v_cvt_pk_bf16_f32 v27, v16, v17
	global_store_dwordx2 v2, v[26:27], s[26:27] offset:2048
	v_pk_mul_f32 v[10:11], v[86:87], v[4:5]
	v_pk_mul_f32 v[10:11], v[10:11], v[150:151]
	v_pk_add_f32 v[12:13], v[216:217], v[6:7]
	v_pk_fma_f32 v[14:15], v[10:11], v[12:13], v[184:185]
	v_pk_mul_f32 v[10:11], v[88:89], v[4:5]
	v_pk_mul_f32 v[10:11], v[10:11], v[152:153]
	v_pk_add_f32 v[12:13], v[218:219], v[6:7]
	v_pk_fma_f32 v[16:17], v[10:11], v[12:13], v[186:187]
	v_cvt_pk_bf16_f32 v28, v14, v15
	v_cvt_pk_bf16_f32 v29, v16, v17
	global_store_dwordx2 v2, v[28:29], s[26:27] offset:2560
	v_pk_mul_f32 v[10:11], v[90:91], v[4:5]
	v_pk_mul_f32 v[10:11], v[10:11], v[156:157]
	v_pk_add_f32 v[12:13], v[220:221], v[6:7]
	v_pk_fma_f32 v[14:15], v[10:11], v[12:13], v[188:189]
	v_pk_mul_f32 v[10:11], v[92:93], v[4:5]
	v_pk_mul_f32 v[10:11], v[10:11], v[158:159]
	v_pk_add_f32 v[12:13], v[222:223], v[6:7]
	v_pk_fma_f32 v[16:17], v[10:11], v[12:13], v[190:191]
	v_cvt_pk_bf16_f32 v30, v14, v15
	v_cvt_pk_bf16_f32 v31, v16, v17
	global_store_dwordx2 v2, v[30:31], s[26:27] offset:3072
	v_pk_mul_f32 v[10:11], v[94:95], v[4:5]
	v_pk_mul_f32 v[10:11], v[10:11], v[160:161]
	v_pk_add_f32 v[12:13], v[224:225], v[6:7]
	v_pk_fma_f32 v[14:15], v[10:11], v[12:13], v[192:193]
	v_pk_mul_f32 v[10:11], v[96:97], v[4:5]
	v_pk_mul_f32 v[10:11], v[10:11], v[162:163]
	v_pk_add_f32 v[12:13], v[226:227], v[6:7]
	v_pk_fma_f32 v[16:17], v[10:11], v[12:13], v[194:195]
	v_cvt_pk_bf16_f32 v32, v14, v15
	v_cvt_pk_bf16_f32 v33, v16, v17
	global_store_dwordx2 v2, v[32:33], s[26:27] offset:3584
	s_waitcnt vmcnt(0)
	s_branch .LBB0_231

.Ltrp1_B:
	s_cmp_ge_u32 s96, 128
	s_cbranch_scc1 .LBB0_257
	s_waitcnt vmcnt(0) lgkmcnt(0)
	s_load_dwordx2 s[0:1], s[92:93], 0x40
	s_load_dwordx2 s[2:3], s[92:93], 0x38
	s_load_dwordx2 s[4:5], s[92:93], 0xf0
	s_load_dwordx2 s[6:7], s[92:93], 0x0
	s_load_dwordx2 s[8:9], s[92:93], 0x8
	v_and_b32_e32 v2, 63, v154
	v_lshlrev_b32_e32 v1, 4, v2
	v_lshlrev_b32_e32 v2, 3, v2
	v_mov_b32_e32 v6, 1.0
	v_mov_b32_e32 v7, 1.0
	s_mov_b32 s40, 0x3a000000
	s_mov_b32 s41, 0x358637bd
	v_readfirstlane_b32 s10, v154
	s_lshr_b32 s10, s10, 6
	s_lshl_b32 s12, s96, 3
	s_add_u32 s10, s10, s12
	s_waitcnt lgkmcnt(0)
	s_add_u32 s12, s10, 0
	s_lshl_b32 s13, s12, 13
	s_lshl_b32 s14, s12, 12
	s_add_u32 s20, s6, s13
	s_addc_u32 s21, s7, 0
	s_add_u32 s22, s90, 0x21918000
	s_addc_u32 s23, s91, 0
	s_add_u32 s22, s22, s14
	s_addc_u32 s23, s23, 0
	s_add_u32 s36, s20, 0x1000
	s_addc_u32 s37, s21, 0
	global_load_dwordx4 v[34:37], v1, s[20:21] nt
	global_load_dwordx4 v[38:41], v1, s[20:21] offset:1024 nt
	global_load_dwordx4 v[42:45], v1, s[20:21] offset:2048 nt
	global_load_dwordx4 v[46:49], v1, s[20:21] offset:3072 nt
	global_load_dwordx4 v[50:53], v1, s[36:37] nt
	global_load_dwordx4 v[54:57], v1, s[36:37] offset:1024 nt
	global_load_dwordx4 v[58:61], v1, s[36:37] offset:2048 nt
	global_load_dwordx4 v[62:65], v1, s[36:37] offset:3072 nt
	s_mov_b32 s16, 4
	s_add_u32 s17, s16, 0
	s_mul_i32 s17, s17, 49152
	s_add_u32 s17, s17, 0x10404000
	s_add_u32 s28, s90, s17
	s_addc_u32 s29, s91, 0
	s_add_u32 s17, s16, 0
	s_mul_i32 s17, s17, 49152
	s_add_u32 s17, s17, 0x10400000
	s_add_u32 s30, s90, s17
	s_addc_u32 s31, s91, 0
	s_add_u32 s32, s30, 0x2000
	s_addc_u32 s33, s31, 0
	s_add_u32 s18, s2, 0x1000
	s_addc_u32 s19, s3, 0
	global_load_dwordx4 v[130:133], v1, s[2:3]
	global_load_dwordx4 v[134:137], v1, s[2:3] offset:1024
	global_load_dwordx4 v[138:141], v1, s[2:3] offset:2048
	global_load_dwordx4 v[142:145], v1, s[2:3] offset:3072
	global_load_dwordx4 v[146:149], v1, s[18:19]
	global_load_dwordx4 v[150:153], v1, s[18:19] offset:1024
	global_load_dwordx4 v[156:159], v1, s[18:19] offset:2048
	global_load_dwordx4 v[160:163], v1, s[18:19] offset:3072
	s_add_u32 s18, s30, 0x1000
	s_addc_u32 s19, s31, 0
	global_load_dwordx4 v[164:167], v1, s[30:31]
	global_load_dwordx4 v[168:171], v1, s[30:31] offset:1024
	global_load_dwordx4 v[172:175], v1, s[30:31] offset:2048
	global_load_dwordx4 v[176:179], v1, s[30:31] offset:3072
	global_load_dwordx4 v[180:183], v1, s[18:19]
	global_load_dwordx4 v[184:187], v1, s[18:19] offset:1024
	global_load_dwordx4 v[188:191], v1, s[18:19] offset:2048
	global_load_dwordx4 v[192:195], v1, s[18:19] offset:3072
	s_add_u32 s18, s32, 0x1000
	s_addc_u32 s19, s33, 0
	global_load_dwordx4 v[196:199], v1, s[32:33]
	global_load_dwordx4 v[200:203], v1, s[32:33] offset:1024
	global_load_dwordx4 v[204:207], v1, s[32:33] offset:2048
	global_load_dwordx4 v[208:211], v1, s[32:33] offset:3072
	global_load_dwordx4 v[212:215], v1, s[18:19]
	global_load_dwordx4 v[216:219], v1, s[18:19] offset:1024
	global_load_dwordx4 v[220:223], v1, s[18:19] offset:2048
	global_load_dwordx4 v[224:227], v1, s[18:19] offset:3072
	s_add_u32 s12, s10, 2048
	s_lshl_b32 s13, s12, 13
	s_lshl_b32 s14, s12, 12
	s_add_u32 s20, s6, s13
	s_addc_u32 s21, s7, 0
	s_add_u32 s22, s90, 0x21918000
	s_addc_u32 s23, s91, 0
	s_add_u32 s22, s22, s14
	s_addc_u32 s23, s23, 0
	s_add_u32 s36, s20, 0x1000
	s_addc_u32 s37, s21, 0
	global_load_dwordx4 v[66:69], v1, s[20:21] nt
	global_load_dwordx4 v[70:73], v1, s[20:21] offset:1024 nt
	global_load_dwordx4 v[74:77], v1, s[20:21] offset:2048 nt
	global_load_dwordx4 v[78:81], v1, s[20:21] offset:3072 nt
	global_load_dwordx4 v[82:85], v1, s[36:37] nt
	global_load_dwordx4 v[86:89], v1, s[36:37] offset:1024 nt
	global_load_dwordx4 v[90:93], v1, s[36:37] offset:2048 nt
	global_load_dwordx4 v[94:97], v1, s[36:37] offset:3072 nt
	s_add_u32 s12, s10, 0
	s_lshl_b32 s14, s12, 12
	s_add_u32 s26, s90, 0x11918000
	s_addc_u32 s27, s91, 0
	s_add_u32 s26, s26, s14
	s_addc_u32 s27, s27, 0
	s_waitcnt vmcnt(32)
	v_mov_b32_e32 v8, 0
	v_fmac_f32_e32 v8, v34, v34
	v_fmac_f32_e32 v8, v35, v35
	v_fmac_f32_e32 v8, v36, v36
	v_fmac_f32_e32 v8, v37, v37
	v_fmac_f32_e32 v8, v38, v38
	v_fmac_f32_e32 v8, v39, v39
	v_fmac_f32_e32 v8, v40, v40
	v_fmac_f32_e32 v8, v41, v41
	v_fmac_f32_e32 v8, v42, v42
	v_fmac_f32_e32 v8, v43, v43
	v_fmac_f32_e32 v8, v44, v44
	v_fmac_f32_e32 v8, v45, v45
	v_fmac_f32_e32 v8, v46, v46
	v_fmac_f32_e32 v8, v47, v47
	v_fmac_f32_e32 v8, v48, v48
	v_fmac_f32_e32 v8, v49, v49
	v_fmac_f32_e32 v8, v50, v50
	v_fmac_f32_e32 v8, v51, v51
	v_fmac_f32_e32 v8, v52, v52
	v_fmac_f32_e32 v8, v53, v53
	v_fmac_f32_e32 v8, v54, v54
	v_fmac_f32_e32 v8, v55, v55
	v_fmac_f32_e32 v8, v56, v56
	v_fmac_f32_e32 v8, v57, v57
	v_fmac_f32_e32 v8, v58, v58
	v_fmac_f32_e32 v8, v59, v59
	v_fmac_f32_e32 v8, v60, v60
	v_fmac_f32_e32 v8, v61, v61
	v_fmac_f32_e32 v8, v62, v62
	v_fmac_f32_e32 v8, v63, v63
	v_fmac_f32_e32 v8, v64, v64
	v_fmac_f32_e32 v8, v65, v65
	s_nop 1
	v_add_f32_dpp v8, v8, v8 quad_perm:[1,0,3,2] row_mask:0xf bank_mask:0xf
	s_nop 1
	v_add_f32_dpp v8, v8, v8 quad_perm:[2,3,0,1] row_mask:0xf bank_mask:0xf
	s_nop 1
	v_add_f32_dpp v8, v8, v8 row_ror:4 row_mask:0xf bank_mask:0xf
	s_nop 1
	v_add_f32_dpp v8, v8, v8 row_ror:8 row_mask:0xf bank_mask:0xf
	s_nop 1
	v_readlane_b32 s42, v8, 0
	v_readlane_b32 s43, v8, 16
	v_readlane_b32 s44, v8, 32
	v_readlane_b32 s45, v8, 48
	s_nop 1
	v_mov_b32_e32 v8, s42
	v_add_f32_e32 v8, s43, v8
	v_add_f32_e32 v8, s44, v8
	v_add_f32_e32 v8, s45, v8
	v_mov_b32_e32 v4, s41
	v_fmac_f32_e32 v4, s40, v8
	v_rsq_f32_e32 v4, v4
	s_nop 0
	v_mov_b32_e32 v5, v4
	s_waitcnt vmcnt(8)
	v_pk_mul_f32 v[10:11], v[34:35], v[4:5]
	v_pk_mul_f32 v[10:11], v[10:11], v[130:131]
	v_pk_add_f32 v[12:13], v[196:197], v[6:7]
	v_pk_fma_f32 v[14:15], v[10:11], v[12:13], v[164:165]
	v_pk_mul_f32 v[10:11], v[36:37], v[4:5]
	v_pk_mul_f32 v[10:11], v[10:11], v[132:133]
	v_pk_add_f32 v[12:13], v[198:199], v[6:7]
	v_pk_fma_f32 v[16:17], v[10:11], v[12:13], v[166:167]
	v_cvt_pk_bf16_f32 v26, v14, v15
	v_cvt_pk_bf16_f32 v27, v16, v17
	global_store_dwordx2 v2, v[26:27], s[26:27]
	v_pk_mul_f32 v[10:11], v[38:39], v[4:5]
	v_pk_mul_f32 v[10:11], v[10:11], v[134:135]
	v_pk_add_f32 v[12:13], v[200:201], v[6:7]
	v_pk_fma_f32 v[14:15], v[10:11], v[12:13], v[168:169]
	v_pk_mul_f32 v[10:11], v[40:41], v[4:5]
	v_pk_mul_f32 v[10:11], v[10:11], v[136:137]
	v_pk_add_f32 v[12:13], v[202:203], v[6:7]
	v_pk_fma_f32 v[16:17], v[10:11], v[12:13], v[170:171]
	v_cvt_pk_bf16_f32 v28, v14, v15
	v_cvt_pk_bf16_f32 v29, v16, v17
	global_store_dwordx2 v2, v[28:29], s[26:27] offset:512
	v_pk_mul_f32 v[10:11], v[42:43], v[4:5]
	v_pk_mul_f32 v[10:11], v[10:11], v[138:139]
	v_pk_add_f32 v[12:13], v[204:205], v[6:7]
	v_pk_fma_f32 v[14:15], v[10:11], v[12:13], v[172:173]
	v_pk_mul_f32 v[10:11], v[44:45], v[4:5]
	v_pk_mul_f32 v[10:11], v[10:11], v[140:141]
	v_pk_add_f32 v[12:13], v[206:207], v[6:7]
	v_pk_fma_f32 v[16:17], v[10:11], v[12:13], v[174:175]
	v_cvt_pk_bf16_f32 v30, v14, v15
	v_cvt_pk_bf16_f32 v31, v16, v17
	global_store_dwordx2 v2, v[30:31], s[26:27] offset:1024
	v_pk_mul_f32 v[10:11], v[46:47], v[4:5]
	v_pk_mul_f32 v[10:11], v[10:11], v[142:143]
	v_pk_add_f32 v[12:13], v[208:209], v[6:7]
	v_pk_fma_f32 v[14:15], v[10:11], v[12:13], v[176:177]
	v_pk_mul_f32 v[10:11], v[48:49], v[4:5]
	v_pk_mul_f32 v[10:11], v[10:11], v[144:145]
	v_pk_add_f32 v[12:13], v[210:211], v[6:7]
	v_pk_fma_f32 v[16:17], v[10:11], v[12:13], v[178:179]
	v_cvt_pk_bf16_f32 v32, v14, v15
	v_cvt_pk_bf16_f32 v33, v16, v17
	global_store_dwordx2 v2, v[32:33], s[26:27] offset:1536
	v_pk_mul_f32 v[10:11], v[50:51], v[4:5]
	v_pk_mul_f32 v[10:11], v[10:11], v[146:147]
	v_pk_add_f32 v[12:13], v[212:213], v[6:7]
	v_pk_fma_f32 v[14:15], v[10:11], v[12:13], v[180:181]
	v_pk_mul_f32 v[10:11], v[52:53], v[4:5]
	v_pk_mul_f32 v[10:11], v[10:11], v[148:149]
	v_pk_add_f32 v[12:13], v[214:215], v[6:7]
	v_pk_fma_f32 v[16:17], v[10:11], v[12:13], v[182:183]
	v_cvt_pk_bf16_f32 v26, v14, v15
	v_cvt_pk_bf16_f32 v27, v16, v17
	global_store_dwordx2 v2, v[26:27], s[26:27] offset:2048
	v_pk_mul_f32 v[10:11], v[54:55], v[4:5]
	v_pk_mul_f32 v[10:11], v[10:11], v[150:151]
	v_pk_add_f32 v[12:13], v[216:217], v[6:7]
	v_pk_fma_f32 v[14:15], v[10:11], v[12:13], v[184:185]
	v_pk_mul_f32 v[10:11], v[56:57], v[4:5]
	v_pk_mul_f32 v[10:11], v[10:11], v[152:153]
	v_pk_add_f32 v[12:13], v[218:219], v[6:7]
	v_pk_fma_f32 v[16:17], v[10:11], v[12:13], v[186:187]
	v_cvt_pk_bf16_f32 v28, v14, v15
	v_cvt_pk_bf16_f32 v29, v16, v17
	global_store_dwordx2 v2, v[28:29], s[26:27] offset:2560
	v_pk_mul_f32 v[10:11], v[58:59], v[4:5]
	v_pk_mul_f32 v[10:11], v[10:11], v[156:157]
	v_pk_add_f32 v[12:13], v[220:221], v[6:7]
	v_pk_fma_f32 v[14:15], v[10:11], v[12:13], v[188:189]
	v_pk_mul_f32 v[10:11], v[60:61], v[4:5]
	v_pk_mul_f32 v[10:11], v[10:11], v[158:159]
	v_pk_add_f32 v[12:13], v[222:223], v[6:7]
	v_pk_fma_f32 v[16:17], v[10:11], v[12:13], v[190:191]
	v_cvt_pk_bf16_f32 v30, v14, v15
	v_cvt_pk_bf16_f32 v31, v16, v17
	global_store_dwordx2 v2, v[30:31], s[26:27] offset:3072
	v_pk_mul_f32 v[10:11], v[62:63], v[4:5]
	v_pk_mul_f32 v[10:11], v[10:11], v[160:161]
	v_pk_add_f32 v[12:13], v[224:225], v[6:7]
	v_pk_fma_f32 v[14:15], v[10:11], v[12:13], v[192:193]
	v_pk_mul_f32 v[10:11], v[64:65], v[4:5]
	v_pk_mul_f32 v[10:11], v[10:11], v[162:163]
	v_pk_add_f32 v[12:13], v[226:227], v[6:7]
	v_pk_fma_f32 v[16:17], v[10:11], v[12:13], v[194:195]
	v_cvt_pk_bf16_f32 v32, v14, v15
	v_cvt_pk_bf16_f32 v33, v16, v17
	global_store_dwordx2 v2, v[32:33], s[26:27] offset:3584
	s_mov_b32 s16, 4
	s_add_u32 s17, s16, 0
	s_mul_i32 s17, s17, 49152
	s_add_u32 s17, s17, 0x10404000
	s_add_u32 s28, s90, s17
	s_addc_u32 s29, s91, 0
	s_add_u32 s17, s16, 0
	s_mul_i32 s17, s17, 49152
	s_add_u32 s17, s17, 0x10400000
	s_add_u32 s30, s90, s17
	s_addc_u32 s31, s91, 0
	s_add_u32 s32, s30, 0x2000
	s_addc_u32 s33, s31, 0
	s_add_u32 s18, s2, 0x1000
	s_addc_u32 s19, s3, 0
	global_load_dwordx4 v[130:133], v1, s[2:3]
	global_load_dwordx4 v[134:137], v1, s[2:3] offset:1024
	global_load_dwordx4 v[138:141], v1, s[2:3] offset:2048
	global_load_dwordx4 v[142:145], v1, s[2:3] offset:3072
	global_load_dwordx4 v[146:149], v1, s[18:19]
	global_load_dwordx4 v[150:153], v1, s[18:19] offset:1024
	global_load_dwordx4 v[156:159], v1, s[18:19] offset:2048
	global_load_dwordx4 v[160:163], v1, s[18:19] offset:3072
	s_add_u32 s18, s30, 0x1000
	s_addc_u32 s19, s31, 0
	global_load_dwordx4 v[164:167], v1, s[30:31]
	global_load_dwordx4 v[168:171], v1, s[30:31] offset:1024
	global_load_dwordx4 v[172:175], v1, s[30:31] offset:2048
	global_load_dwordx4 v[176:179], v1, s[30:31] offset:3072
	global_load_dwordx4 v[180:183], v1, s[18:19]
	global_load_dwordx4 v[184:187], v1, s[18:19] offset:1024
	global_load_dwordx4 v[188:191], v1, s[18:19] offset:2048
	global_load_dwordx4 v[192:195], v1, s[18:19] offset:3072
	s_add_u32 s18, s32, 0x1000
	s_addc_u32 s19, s33, 0
	global_load_dwordx4 v[196:199], v1, s[32:33]
	global_load_dwordx4 v[200:203], v1, s[32:33] offset:1024
	global_load_dwordx4 v[204:207], v1, s[32:33] offset:2048
	global_load_dwordx4 v[208:211], v1, s[32:33] offset:3072
	global_load_dwordx4 v[212:215], v1, s[18:19]
	global_load_dwordx4 v[216:219], v1, s[18:19] offset:1024
	global_load_dwordx4 v[220:223], v1, s[18:19] offset:2048
	global_load_dwordx4 v[224:227], v1, s[18:19] offset:3072
	s_add_u32 s12, s10, 4096
	s_lshl_b32 s13, s12, 13
	s_lshl_b32 s14, s12, 12
	s_sub_u32 s15, s13, 0x2000000
	s_add_u32 s20, s8, s15
	s_addc_u32 s21, s9, 0
	s_add_u32 s22, s90, 0x21918000
	s_addc_u32 s23, s91, 0
	s_add_u32 s22, s22, s14
	s_addc_u32 s23, s23, 0
	s_add_u32 s36, s20, 0x1000
	s_addc_u32 s37, s21, 0
	global_load_dwordx4 v[34:37], v1, s[20:21] nt
	global_load_dwordx4 v[38:41], v1, s[20:21] offset:1024 nt
	global_load_dwordx4 v[42:45], v1, s[20:21] offset:2048 nt
	global_load_dwordx4 v[46:49], v1, s[20:21] offset:3072 nt
	global_load_dwordx4 v[50:53], v1, s[36:37] nt
	global_load_dwordx4 v[54:57], v1, s[36:37] offset:1024 nt
	global_load_dwordx4 v[58:61], v1, s[36:37] offset:2048 nt
	global_load_dwordx4 v[62:65], v1, s[36:37] offset:3072 nt
	s_add_u32 s12, s10, 2048
	s_lshl_b32 s14, s12, 12
	s_add_u32 s26, s90, 0x11918000
	s_addc_u32 s27, s91, 0
	s_add_u32 s26, s26, s14
	s_addc_u32 s27, s27, 0
	s_waitcnt vmcnt(40)
	v_mov_b32_e32 v8, 0
	v_fmac_f32_e32 v8, v66, v66
	v_fmac_f32_e32 v8, v67, v67
	v_fmac_f32_e32 v8, v68, v68
	v_fmac_f32_e32 v8, v69, v69
	v_fmac_f32_e32 v8, v70, v70
	v_fmac_f32_e32 v8, v71, v71
	v_fmac_f32_e32 v8, v72, v72
	v_fmac_f32_e32 v8, v73, v73
	v_fmac_f32_e32 v8, v74, v74
	v_fmac_f32_e32 v8, v75, v75
	v_fmac_f32_e32 v8, v76, v76
	v_fmac_f32_e32 v8, v77, v77
	v_fmac_f32_e32 v8, v78, v78
	v_fmac_f32_e32 v8, v79, v79
	v_fmac_f32_e32 v8, v80, v80
	v_fmac_f32_e32 v8, v81, v81
	v_fmac_f32_e32 v8, v82, v82
	v_fmac_f32_e32 v8, v83, v83
	v_fmac_f32_e32 v8, v84, v84
	v_fmac_f32_e32 v8, v85, v85
	v_fmac_f32_e32 v8, v86, v86
	v_fmac_f32_e32 v8, v87, v87
	v_fmac_f32_e32 v8, v88, v88
	v_fmac_f32_e32 v8, v89, v89
	v_fmac_f32_e32 v8, v90, v90
	v_fmac_f32_e32 v8, v91, v91
	v_fmac_f32_e32 v8, v92, v92
	v_fmac_f32_e32 v8, v93, v93
	v_fmac_f32_e32 v8, v94, v94
	v_fmac_f32_e32 v8, v95, v95
	v_fmac_f32_e32 v8, v96, v96
	v_fmac_f32_e32 v8, v97, v97
	s_nop 1
	v_add_f32_dpp v8, v8, v8 quad_perm:[1,0,3,2] row_mask:0xf bank_mask:0xf
	s_nop 1
	v_add_f32_dpp v8, v8, v8 quad_perm:[2,3,0,1] row_mask:0xf bank_mask:0xf
	s_nop 1
	v_add_f32_dpp v8, v8, v8 row_ror:4 row_mask:0xf bank_mask:0xf
	s_nop 1
	v_add_f32_dpp v8, v8, v8 row_ror:8 row_mask:0xf bank_mask:0xf
	s_nop 1
	v_readlane_b32 s42, v8, 0
	v_readlane_b32 s43, v8, 16
	v_readlane_b32 s44, v8, 32
	v_readlane_b32 s45, v8, 48
	s_nop 1
	v_mov_b32_e32 v8, s42
	v_add_f32_e32 v8, s43, v8
	v_add_f32_e32 v8, s44, v8
	v_add_f32_e32 v8, s45, v8
	v_mov_b32_e32 v4, s41
	v_fmac_f32_e32 v4, s40, v8
	v_rsq_f32_e32 v4, v4
	s_nop 0
	v_mov_b32_e32 v5, v4
	s_waitcnt vmcnt(8)
	v_pk_mul_f32 v[10:11], v[66:67], v[4:5]
	v_pk_mul_f32 v[10:11], v[10:11], v[130:131]
	v_pk_add_f32 v[12:13], v[196:197], v[6:7]
	v_pk_fma_f32 v[14:15], v[10:11], v[12:13], v[164:165]
	v_pk_mul_f32 v[10:11], v[68:69], v[4:5]
	v_pk_mul_f32 v[10:11], v[10:11], v[132:133]
	v_pk_add_f32 v[12:13], v[198:199], v[6:7]
	v_pk_fma_f32 v[16:17], v[10:11], v[12:13], v[166:167]
	v_cvt_pk_bf16_f32 v26, v14, v15
	v_cvt_pk_bf16_f32 v27, v16, v17
	global_store_dwordx2 v2, v[26:27], s[26:27]
	v_pk_mul_f32 v[10:11], v[70:71], v[4:5]
	v_pk_mul_f32 v[10:11], v[10:11], v[134:135]
	v_pk_add_f32 v[12:13], v[200:201], v[6:7]
	v_pk_fma_f32 v[14:15], v[10:11], v[12:13], v[168:169]
	v_pk_mul_f32 v[10:11], v[72:73], v[4:5]
	v_pk_mul_f32 v[10:11], v[10:11], v[136:137]
	v_pk_add_f32 v[12:13], v[202:203], v[6:7]
	v_pk_fma_f32 v[16:17], v[10:11], v[12:13], v[170:171]
	v_cvt_pk_bf16_f32 v28, v14, v15
	v_cvt_pk_bf16_f32 v29, v16, v17
	global_store_dwordx2 v2, v[28:29], s[26:27] offset:512
	v_pk_mul_f32 v[10:11], v[74:75], v[4:5]
	v_pk_mul_f32 v[10:11], v[10:11], v[138:139]
	v_pk_add_f32 v[12:13], v[204:205], v[6:7]
	v_pk_fma_f32 v[14:15], v[10:11], v[12:13], v[172:173]
	v_pk_mul_f32 v[10:11], v[76:77], v[4:5]
	v_pk_mul_f32 v[10:11], v[10:11], v[140:141]
	v_pk_add_f32 v[12:13], v[206:207], v[6:7]
	v_pk_fma_f32 v[16:17], v[10:11], v[12:13], v[174:175]
	v_cvt_pk_bf16_f32 v30, v14, v15
	v_cvt_pk_bf16_f32 v31, v16, v17
	global_store_dwordx2 v2, v[30:31], s[26:27] offset:1024
	v_pk_mul_f32 v[10:11], v[78:79], v[4:5]
	v_pk_mul_f32 v[10:11], v[10:11], v[142:143]
	v_pk_add_f32 v[12:13], v[208:209], v[6:7]
	v_pk_fma_f32 v[14:15], v[10:11], v[12:13], v[176:177]
	v_pk_mul_f32 v[10:11], v[80:81], v[4:5]
	v_pk_mul_f32 v[10:11], v[10:11], v[144:145]
	v_pk_add_f32 v[12:13], v[210:211], v[6:7]
	v_pk_fma_f32 v[16:17], v[10:11], v[12:13], v[178:179]
	v_cvt_pk_bf16_f32 v32, v14, v15
	v_cvt_pk_bf16_f32 v33, v16, v17
	global_store_dwordx2 v2, v[32:33], s[26:27] offset:1536
	v_pk_mul_f32 v[10:11], v[82:83], v[4:5]
	v_pk_mul_f32 v[10:11], v[10:11], v[146:147]
	v_pk_add_f32 v[12:13], v[212:213], v[6:7]
	v_pk_fma_f32 v[14:15], v[10:11], v[12:13], v[180:181]
	v_pk_mul_f32 v[10:11], v[84:85], v[4:5]
	v_pk_mul_f32 v[10:11], v[10:11], v[148:149]
	v_pk_add_f32 v[12:13], v[214:215], v[6:7]
	v_pk_fma_f32 v[16:17], v[10:11], v[12:13], v[182:183]
	v_cvt_pk_bf16_f32 v26, v14, v15
	v_cvt_pk_bf16_f32 v27, v16, v17
	global_store_dwordx2 v2, v[26:27], s[26:27] offset:2048
	v_pk_mul_f32 v[10:11], v[86:87], v[4:5]
	v_pk_mul_f32 v[10:11], v[10:11], v[150:151]
	v_pk_add_f32 v[12:13], v[216:217], v[6:7]
	v_pk_fma_f32 v[14:15], v[10:11], v[12:13], v[184:185]
	v_pk_mul_f32 v[10:11], v[88:89], v[4:5]
	v_pk_mul_f32 v[10:11], v[10:11], v[152:153]
	v_pk_add_f32 v[12:13], v[218:219], v[6:7]
	v_pk_fma_f32 v[16:17], v[10:11], v[12:13], v[186:187]
	v_cvt_pk_bf16_f32 v28, v14, v15
	v_cvt_pk_bf16_f32 v29, v16, v17
	global_store_dwordx2 v2, v[28:29], s[26:27] offset:2560
	v_pk_mul_f32 v[10:11], v[90:91], v[4:5]
	v_pk_mul_f32 v[10:11], v[10:11], v[156:157]
	v_pk_add_f32 v[12:13], v[220:221], v[6:7]
	v_pk_fma_f32 v[14:15], v[10:11], v[12:13], v[188:189]
	v_pk_mul_f32 v[10:11], v[92:93], v[4:5]
	v_pk_mul_f32 v[10:11], v[10:11], v[158:159]
	v_pk_add_f32 v[12:13], v[222:223], v[6:7]
	v_pk_fma_f32 v[16:17], v[10:11], v[12:13], v[190:191]
	v_cvt_pk_bf16_f32 v30, v14, v15
	v_cvt_pk_bf16_f32 v31, v16, v17
	global_store_dwordx2 v2, v[30:31], s[26:27] offset:3072
	v_pk_mul_f32 v[10:11], v[94:95], v[4:5]
	v_pk_mul_f32 v[10:11], v[10:11], v[160:161]
	v_pk_add_f32 v[12:13], v[224:225], v[6:7]
	v_pk_fma_f32 v[14:15], v[10:11], v[12:13], v[192:193]
	v_pk_mul_f32 v[10:11], v[96:97], v[4:5]
	v_pk_mul_f32 v[10:11], v[10:11], v[162:163]
	v_pk_add_f32 v[12:13], v[226:227], v[6:7]
	v_pk_fma_f32 v[16:17], v[10:11], v[12:13], v[194:195]
	v_cvt_pk_bf16_f32 v32, v14, v15
	v_cvt_pk_bf16_f32 v33, v16, v17
	global_store_dwordx2 v2, v[32:33], s[26:27] offset:3584
	s_lshr_b32 s16, s10, 10
	s_add_u32 s17, s16, 0
	s_mul_i32 s17, s17, 49152
	s_add_u32 s17, s17, 0x10404000
	s_add_u32 s28, s90, s17
	s_addc_u32 s29, s91, 0
	s_add_u32 s17, s16, 0
	s_mul_i32 s17, s17, 49152
	s_add_u32 s17, s17, 0x10400000
	s_add_u32 s30, s90, s17
	s_addc_u32 s31, s91, 0
	s_add_u32 s32, s30, 0x2000
	s_addc_u32 s33, s31, 0
	s_add_u32 s18, s2, 0x1000
	s_addc_u32 s19, s3, 0
	global_load_dwordx4 v[130:133], v1, s[2:3]
	global_load_dwordx4 v[134:137], v1, s[2:3] offset:1024
	global_load_dwordx4 v[138:141], v1, s[2:3] offset:2048
	global_load_dwordx4 v[142:145], v1, s[2:3] offset:3072
	global_load_dwordx4 v[146:149], v1, s[18:19]
	global_load_dwordx4 v[150:153], v1, s[18:19] offset:1024
	global_load_dwordx4 v[156:159], v1, s[18:19] offset:2048
	global_load_dwordx4 v[160:163], v1, s[18:19] offset:3072
	s_add_u32 s18, s30, 0x1000
	s_addc_u32 s19, s31, 0
	global_load_dwordx4 v[164:167], v1, s[30:31]
	global_load_dwordx4 v[168:171], v1, s[30:31] offset:1024
	global_load_dwordx4 v[172:175], v1, s[30:31] offset:2048
	global_load_dwordx4 v[176:179], v1, s[30:31] offset:3072
	global_load_dwordx4 v[180:183], v1, s[18:19]
	global_load_dwordx4 v[184:187], v1, s[18:19] offset:1024
	global_load_dwordx4 v[188:191], v1, s[18:19] offset:2048
	global_load_dwordx4 v[192:195], v1, s[18:19] offset:3072
	s_add_u32 s18, s32, 0x1000
	s_addc_u32 s19, s33, 0
	global_load_dwordx4 v[196:199], v1, s[32:33]
	global_load_dwordx4 v[200:203], v1, s[32:33] offset:1024
	global_load_dwordx4 v[204:207], v1, s[32:33] offset:2048
	global_load_dwordx4 v[208:211], v1, s[32:33] offset:3072
	global_load_dwordx4 v[212:215], v1, s[18:19]
	global_load_dwordx4 v[216:219], v1, s[18:19] offset:1024
	global_load_dwordx4 v[220:223], v1, s[18:19] offset:2048
	global_load_dwordx4 v[224:227], v1, s[18:19] offset:3072
	s_add_u32 s12, s10, 6144
	s_lshl_b32 s13, s12, 13
	s_lshl_b32 s14, s12, 12
	s_sub_u32 s15, s13, 0x2000000
	s_add_u32 s20, s8, s15
	s_addc_u32 s21, s9, 0
	s_add_u32 s22, s90, 0x21918000
	s_addc_u32 s23, s91, 0
	s_add_u32 s22, s22, s14
	s_addc_u32 s23, s23, 0
	s_add_u32 s36, s20, 0x1000
	s_addc_u32 s37, s21, 0
	global_load_dwordx4 v[66:69], v1, s[20:21] nt
	global_load_dwordx4 v[70:73], v1, s[20:21] offset:1024 nt
	global_load_dwordx4 v[74:77], v1, s[20:21] offset:2048 nt
	global_load_dwordx4 v[78:81], v1, s[20:21] offset:3072 nt
	global_load_dwordx4 v[82:85], v1, s[36:37] nt
	global_load_dwordx4 v[86:89], v1, s[36:37] offset:1024 nt
	global_load_dwordx4 v[90:93], v1, s[36:37] offset:2048 nt
	global_load_dwordx4 v[94:97], v1, s[36:37] offset:3072 nt
	s_add_u32 s12, s10, 4096
	s_lshl_b32 s14, s12, 12
	s_add_u32 s26, s90, 0x11918000
	s_addc_u32 s27, s91, 0
	s_add_u32 s26, s26, s14
	s_addc_u32 s27, s27, 0
	s_waitcnt vmcnt(40)
	v_mov_b32_e32 v8, 0
	v_fmac_f32_e32 v8, v34, v34
	v_fmac_f32_e32 v8, v35, v35
	v_fmac_f32_e32 v8, v36, v36
	v_fmac_f32_e32 v8, v37, v37
	v_fmac_f32_e32 v8, v38, v38
	v_fmac_f32_e32 v8, v39, v39
	v_fmac_f32_e32 v8, v40, v40
	v_fmac_f32_e32 v8, v41, v41
	v_fmac_f32_e32 v8, v42, v42
	v_fmac_f32_e32 v8, v43, v43
	v_fmac_f32_e32 v8, v44, v44
	v_fmac_f32_e32 v8, v45, v45
	v_fmac_f32_e32 v8, v46, v46
	v_fmac_f32_e32 v8, v47, v47
	v_fmac_f32_e32 v8, v48, v48
	v_fmac_f32_e32 v8, v49, v49
	v_fmac_f32_e32 v8, v50, v50
	v_fmac_f32_e32 v8, v51, v51
	v_fmac_f32_e32 v8, v52, v52
	v_fmac_f32_e32 v8, v53, v53
	v_fmac_f32_e32 v8, v54, v54
	v_fmac_f32_e32 v8, v55, v55
	v_fmac_f32_e32 v8, v56, v56
	v_fmac_f32_e32 v8, v57, v57
	v_fmac_f32_e32 v8, v58, v58
	v_fmac_f32_e32 v8, v59, v59
	v_fmac_f32_e32 v8, v60, v60
	v_fmac_f32_e32 v8, v61, v61
	v_fmac_f32_e32 v8, v62, v62
	v_fmac_f32_e32 v8, v63, v63
	v_fmac_f32_e32 v8, v64, v64
	v_fmac_f32_e32 v8, v65, v65
	s_nop 1
	v_add_f32_dpp v8, v8, v8 quad_perm:[1,0,3,2] row_mask:0xf bank_mask:0xf
	s_nop 1
	v_add_f32_dpp v8, v8, v8 quad_perm:[2,3,0,1] row_mask:0xf bank_mask:0xf
	s_nop 1
	v_add_f32_dpp v8, v8, v8 row_ror:4 row_mask:0xf bank_mask:0xf
	s_nop 1
	v_add_f32_dpp v8, v8, v8 row_ror:8 row_mask:0xf bank_mask:0xf
	s_nop 1
	v_readlane_b32 s42, v8, 0
	v_readlane_b32 s43, v8, 16
	v_readlane_b32 s44, v8, 32
	v_readlane_b32 s45, v8, 48
	s_nop 1
	v_mov_b32_e32 v8, s42
	v_add_f32_e32 v8, s43, v8
	v_add_f32_e32 v8, s44, v8
	v_add_f32_e32 v8, s45, v8
	v_mov_b32_e32 v4, s41
	v_fmac_f32_e32 v4, s40, v8
	v_rsq_f32_e32 v4, v4
	s_nop 0
	v_mov_b32_e32 v5, v4
	s_waitcnt vmcnt(8)
	v_pk_mul_f32 v[10:11], v[34:35], v[4:5]
	v_pk_mul_f32 v[10:11], v[10:11], v[130:131]
	v_pk_add_f32 v[12:13], v[196:197], v[6:7]
	v_pk_fma_f32 v[14:15], v[10:11], v[12:13], v[164:165]
	v_pk_mul_f32 v[10:11], v[36:37], v[4:5]
	v_pk_mul_f32 v[10:11], v[10:11], v[132:133]
	v_pk_add_f32 v[12:13], v[198:199], v[6:7]
	v_pk_fma_f32 v[16:17], v[10:11], v[12:13], v[166:167]
	v_cvt_pk_bf16_f32 v26, v14, v15
	v_cvt_pk_bf16_f32 v27, v16, v17
	global_store_dwordx2 v2, v[26:27], s[26:27]
	v_pk_mul_f32 v[10:11], v[38:39], v[4:5]
	v_pk_mul_f32 v[10:11], v[10:11], v[134:135]
	v_pk_add_f32 v[12:13], v[200:201], v[6:7]
	v_pk_fma_f32 v[14:15], v[10:11], v[12:13], v[168:169]
	v_pk_mul_f32 v[10:11], v[40:41], v[4:5]
	v_pk_mul_f32 v[10:11], v[10:11], v[136:137]
	v_pk_add_f32 v[12:13], v[202:203], v[6:7]
	v_pk_fma_f32 v[16:17], v[10:11], v[12:13], v[170:171]
	v_cvt_pk_bf16_f32 v28, v14, v15
	v_cvt_pk_bf16_f32 v29, v16, v17
	global_store_dwordx2 v2, v[28:29], s[26:27] offset:512
	v_pk_mul_f32 v[10:11], v[42:43], v[4:5]
	v_pk_mul_f32 v[10:11], v[10:11], v[138:139]
	v_pk_add_f32 v[12:13], v[204:205], v[6:7]
	v_pk_fma_f32 v[14:15], v[10:11], v[12:13], v[172:173]
	v_pk_mul_f32 v[10:11], v[44:45], v[4:5]
	v_pk_mul_f32 v[10:11], v[10:11], v[140:141]
	v_pk_add_f32 v[12:13], v[206:207], v[6:7]
	v_pk_fma_f32 v[16:17], v[10:11], v[12:13], v[174:175]
	v_cvt_pk_bf16_f32 v30, v14, v15
	v_cvt_pk_bf16_f32 v31, v16, v17
	global_store_dwordx2 v2, v[30:31], s[26:27] offset:1024
	v_pk_mul_f32 v[10:11], v[46:47], v[4:5]
	v_pk_mul_f32 v[10:11], v[10:11], v[142:143]
	v_pk_add_f32 v[12:13], v[208:209], v[6:7]
	v_pk_fma_f32 v[14:15], v[10:11], v[12:13], v[176:177]
	v_pk_mul_f32 v[10:11], v[48:49], v[4:5]
	v_pk_mul_f32 v[10:11], v[10:11], v[144:145]
	v_pk_add_f32 v[12:13], v[210:211], v[6:7]
	v_pk_fma_f32 v[16:17], v[10:11], v[12:13], v[178:179]
	v_cvt_pk_bf16_f32 v32, v14, v15
	v_cvt_pk_bf16_f32 v33, v16, v17
	global_store_dwordx2 v2, v[32:33], s[26:27] offset:1536
	v_pk_mul_f32 v[10:11], v[50:51], v[4:5]
	v_pk_mul_f32 v[10:11], v[10:11], v[146:147]
	v_pk_add_f32 v[12:13], v[212:213], v[6:7]
	v_pk_fma_f32 v[14:15], v[10:11], v[12:13], v[180:181]
	v_pk_mul_f32 v[10:11], v[52:53], v[4:5]
	v_pk_mul_f32 v[10:11], v[10:11], v[148:149]
	v_pk_add_f32 v[12:13], v[214:215], v[6:7]
	v_pk_fma_f32 v[16:17], v[10:11], v[12:13], v[182:183]
	v_cvt_pk_bf16_f32 v26, v14, v15
	v_cvt_pk_bf16_f32 v27, v16, v17
	global_store_dwordx2 v2, v[26:27], s[26:27] offset:2048
	v_pk_mul_f32 v[10:11], v[54:55], v[4:5]
	v_pk_mul_f32 v[10:11], v[10:11], v[150:151]
	v_pk_add_f32 v[12:13], v[216:217], v[6:7]
	v_pk_fma_f32 v[14:15], v[10:11], v[12:13], v[184:185]
	v_pk_mul_f32 v[10:11], v[56:57], v[4:5]
	v_pk_mul_f32 v[10:11], v[10:11], v[152:153]
	v_pk_add_f32 v[12:13], v[218:219], v[6:7]
	v_pk_fma_f32 v[16:17], v[10:11], v[12:13], v[186:187]
	v_cvt_pk_bf16_f32 v28, v14, v15
	v_cvt_pk_bf16_f32 v29, v16, v17
	global_store_dwordx2 v2, v[28:29], s[26:27] offset:2560
	v_pk_mul_f32 v[10:11], v[58:59], v[4:5]
	v_pk_mul_f32 v[10:11], v[10:11], v[156:157]
	v_pk_add_f32 v[12:13], v[220:221], v[6:7]
	v_pk_fma_f32 v[14:15], v[10:11], v[12:13], v[188:189]
	v_pk_mul_f32 v[10:11], v[60:61], v[4:5]
	v_pk_mul_f32 v[10:11], v[10:11], v[158:159]
	v_pk_add_f32 v[12:13], v[222:223], v[6:7]
	v_pk_fma_f32 v[16:17], v[10:11], v[12:13], v[190:191]
	v_cvt_pk_bf16_f32 v30, v14, v15
	v_cvt_pk_bf16_f32 v31, v16, v17
	global_store_dwordx2 v2, v[30:31], s[26:27] offset:3072
	v_pk_mul_f32 v[10:11], v[62:63], v[4:5]
	v_pk_mul_f32 v[10:11], v[10:11], v[160:161]
	v_pk_add_f32 v[12:13], v[224:225], v[6:7]
	v_pk_fma_f32 v[14:15], v[10:11], v[12:13], v[192:193]
	v_pk_mul_f32 v[10:11], v[64:65], v[4:5]
	v_pk_mul_f32 v[10:11], v[10:11], v[162:163]
	v_pk_add_f32 v[12:13], v[226:227], v[6:7]
	v_pk_fma_f32 v[16:17], v[10:11], v[12:13], v[194:195]
	v_cvt_pk_bf16_f32 v32, v14, v15
	v_cvt_pk_bf16_f32 v33, v16, v17
	global_store_dwordx2 v2, v[32:33], s[26:27] offset:3584
	s_lshr_b32 s16, s10, 10
	s_add_u32 s16, s16, 2
	s_add_u32 s17, s16, 0
	s_mul_i32 s17, s17, 49152
	s_add_u32 s17, s17, 0x10404000
	s_add_u32 s28, s90, s17
	s_addc_u32 s29, s91, 0
	s_add_u32 s17, s16, 0
	s_mul_i32 s17, s17, 49152
	s_add_u32 s17, s17, 0x10400000
	s_add_u32 s30, s90, s17
	s_addc_u32 s31, s91, 0
	s_add_u32 s32, s30, 0x2000
	s_addc_u32 s33, s31, 0
	s_add_u32 s18, s2, 0x1000
	s_addc_u32 s19, s3, 0
	global_load_dwordx4 v[130:133], v1, s[2:3]
	global_load_dwordx4 v[134:137], v1, s[2:3] offset:1024
	global_load_dwordx4 v[138:141], v1, s[2:3] offset:2048
	global_load_dwordx4 v[142:145], v1, s[2:3] offset:3072
	global_load_dwordx4 v[146:149], v1, s[18:19]
	global_load_dwordx4 v[150:153], v1, s[18:19] offset:1024
	global_load_dwordx4 v[156:159], v1, s[18:19] offset:2048
	global_load_dwordx4 v[160:163], v1, s[18:19] offset:3072
	s_add_u32 s18, s30, 0x1000
	s_addc_u32 s19, s31, 0
	global_load_dwordx4 v[164:167], v1, s[30:31]
	global_load_dwordx4 v[168:171], v1, s[30:31] offset:1024
	global_load_dwordx4 v[172:175], v1, s[30:31] offset:2048
	global_load_dwordx4 v[176:179], v1, s[30:31] offset:3072
	global_load_dwordx4 v[180:183], v1, s[18:19]
	global_load_dwordx4 v[184:187], v1, s[18:19] offset:1024
	global_load_dwordx4 v[188:191], v1, s[18:19] offset:2048
	global_load_dwordx4 v[192:195], v1, s[18:19] offset:3072
	s_add_u32 s18, s32, 0x1000
	s_addc_u32 s19, s33, 0
	global_load_dwordx4 v[196:199], v1, s[32:33]
	global_load_dwordx4 v[200:203], v1, s[32:33] offset:1024
	global_load_dwordx4 v[204:207], v1, s[32:33] offset:2048
	global_load_dwordx4 v[208:211], v1, s[32:33] offset:3072
	global_load_dwordx4 v[212:215], v1, s[18:19]
	global_load_dwordx4 v[216:219], v1, s[18:19] offset:1024
	global_load_dwordx4 v[220:223], v1, s[18:19] offset:2048
	global_load_dwordx4 v[224:227], v1, s[18:19] offset:3072
	s_add_u32 s12, s10, 6144
	s_lshl_b32 s14, s12, 12
	s_add_u32 s26, s90, 0x11918000
	s_addc_u32 s27, s91, 0
	s_add_u32 s26, s26, s14
	s_addc_u32 s27, s27, 0
	s_waitcnt vmcnt(32)
	v_mov_b32_e32 v8, 0
	v_fmac_f32_e32 v8, v66, v66
	v_fmac_f32_e32 v8, v67, v67
	v_fmac_f32_e32 v8, v68, v68
	v_fmac_f32_e32 v8, v69, v69
	v_fmac_f32_e32 v8, v70, v70
	v_fmac_f32_e32 v8, v71, v71
	v_fmac_f32_e32 v8, v72, v72
	v_fmac_f32_e32 v8, v73, v73
	v_fmac_f32_e32 v8, v74, v74
	v_fmac_f32_e32 v8, v75, v75
	v_fmac_f32_e32 v8, v76, v76
	v_fmac_f32_e32 v8, v77, v77
	v_fmac_f32_e32 v8, v78, v78
	v_fmac_f32_e32 v8, v79, v79
	v_fmac_f32_e32 v8, v80, v80
	v_fmac_f32_e32 v8, v81, v81
	v_fmac_f32_e32 v8, v82, v82
	v_fmac_f32_e32 v8, v83, v83
	v_fmac_f32_e32 v8, v84, v84
	v_fmac_f32_e32 v8, v85, v85
	v_fmac_f32_e32 v8, v86, v86
	v_fmac_f32_e32 v8, v87, v87
	v_fmac_f32_e32 v8, v88, v88
	v_fmac_f32_e32 v8, v89, v89
	v_fmac_f32_e32 v8, v90, v90
	v_fmac_f32_e32 v8, v91, v91
	v_fmac_f32_e32 v8, v92, v92
	v_fmac_f32_e32 v8, v93, v93
	v_fmac_f32_e32 v8, v94, v94
	v_fmac_f32_e32 v8, v95, v95
	v_fmac_f32_e32 v8, v96, v96
	v_fmac_f32_e32 v8, v97, v97
	s_nop 1
	v_add_f32_dpp v8, v8, v8 quad_perm:[1,0,3,2] row_mask:0xf bank_mask:0xf
	s_nop 1
	v_add_f32_dpp v8, v8, v8 quad_perm:[2,3,0,1] row_mask:0xf bank_mask:0xf
	s_nop 1
	v_add_f32_dpp v8, v8, v8 row_ror:4 row_mask:0xf bank_mask:0xf
	s_nop 1
	v_add_f32_dpp v8, v8, v8 row_ror:8 row_mask:0xf bank_mask:0xf
	s_nop 1
	v_readlane_b32 s42, v8, 0
	v_readlane_b32 s43, v8, 16
	v_readlane_b32 s44, v8, 32
	v_readlane_b32 s45, v8, 48
	s_nop 1
	v_mov_b32_e32 v8, s42
	v_add_f32_e32 v8, s43, v8
	v_add_f32_e32 v8, s44, v8
	v_add_f32_e32 v8, s45, v8
	v_mov_b32_e32 v4, s41
	v_fmac_f32_e32 v4, s40, v8
	v_rsq_f32_e32 v4, v4
	s_nop 0
	v_mov_b32_e32 v5, v4
	s_waitcnt vmcnt(0)
	v_pk_mul_f32 v[10:11], v[66:67], v[4:5]
	v_pk_mul_f32 v[10:11], v[10:11], v[130:131]
	v_pk_add_f32 v[12:13], v[196:197], v[6:7]
	v_pk_fma_f32 v[14:15], v[10:11], v[12:13], v[164:165]
	v_pk_mul_f32 v[10:11], v[68:69], v[4:5]
	v_pk_mul_f32 v[10:11], v[10:11], v[132:133]
	v_pk_add_f32 v[12:13], v[198:199], v[6:7]
	v_pk_fma_f32 v[16:17], v[10:11], v[12:13], v[166:167]
	v_cvt_pk_bf16_f32 v26, v14, v15
	v_cvt_pk_bf16_f32 v27, v16, v17
	global_store_dwordx2 v2, v[26:27], s[26:27]
	v_pk_mul_f32 v[10:11], v[70:71], v[4:5]
	v_pk_mul_f32 v[10:11], v[10:11], v[134:135]
	v_pk_add_f32 v[12:13], v[200:201], v[6:7]
	v_pk_fma_f32 v[14:15], v[10:11], v[12:13], v[168:169]
	v_pk_mul_f32 v[10:11], v[72:73], v[4:5]
	v_pk_mul_f32 v[10:11], v[10:11], v[136:137]
	v_pk_add_f32 v[12:13], v[202:203], v[6:7]
	v_pk_fma_f32 v[16:17], v[10:11], v[12:13], v[170:171]
	v_cvt_pk_bf16_f32 v28, v14, v15
	v_cvt_pk_bf16_f32 v29, v16, v17
	global_store_dwordx2 v2, v[28:29], s[26:27] offset:512
	v_pk_mul_f32 v[10:11], v[74:75], v[4:5]
	v_pk_mul_f32 v[10:11], v[10:11], v[138:139]
	v_pk_add_f32 v[12:13], v[204:205], v[6:7]
	v_pk_fma_f32 v[14:15], v[10:11], v[12:13], v[172:173]
	v_pk_mul_f32 v[10:11], v[76:77], v[4:5]
	v_pk_mul_f32 v[10:11], v[10:11], v[140:141]
	v_pk_add_f32 v[12:13], v[206:207], v[6:7]
	v_pk_fma_f32 v[16:17], v[10:11], v[12:13], v[174:175]
	v_cvt_pk_bf16_f32 v30, v14, v15
	v_cvt_pk_bf16_f32 v31, v16, v17
	global_store_dwordx2 v2, v[30:31], s[26:27] offset:1024
	v_pk_mul_f32 v[10:11], v[78:79], v[4:5]
	v_pk_mul_f32 v[10:11], v[10:11], v[142:143]
	v_pk_add_f32 v[12:13], v[208:209], v[6:7]
	v_pk_fma_f32 v[14:15], v[10:11], v[12:13], v[176:177]
	v_pk_mul_f32 v[10:11], v[80:81], v[4:5]
	v_pk_mul_f32 v[10:11], v[10:11], v[144:145]
	v_pk_add_f32 v[12:13], v[210:211], v[6:7]
	v_pk_fma_f32 v[16:17], v[10:11], v[12:13], v[178:179]
	v_cvt_pk_bf16_f32 v32, v14, v15
	v_cvt_pk_bf16_f32 v33, v16, v17
	global_store_dwordx2 v2, v[32:33], s[26:27] offset:1536
	v_pk_mul_f32 v[10:11], v[82:83], v[4:5]
	v_pk_mul_f32 v[10:11], v[10:11], v[146:147]
	v_pk_add_f32 v[12:13], v[212:213], v[6:7]
	v_pk_fma_f32 v[14:15], v[10:11], v[12:13], v[180:181]
	v_pk_mul_f32 v[10:11], v[84:85], v[4:5]
	v_pk_mul_f32 v[10:11], v[10:11], v[148:149]
	v_pk_add_f32 v[12:13], v[214:215], v[6:7]
	v_pk_fma_f32 v[16:17], v[10:11], v[12:13], v[182:183]
	v_cvt_pk_bf16_f32 v26, v14, v15
	v_cvt_pk_bf16_f32 v27, v16, v17
	global_store_dwordx2 v2, v[26:27], s[26:27] offset:2048
	v_pk_mul_f32 v[10:11], v[86:87], v[4:5]
	v_pk_mul_f32 v[10:11], v[10:11], v[150:151]
	v_pk_add_f32 v[12:13], v[216:217], v[6:7]
	v_pk_fma_f32 v[14:15], v[10:11], v[12:13], v[184:185]
	v_pk_mul_f32 v[10:11], v[88:89], v[4:5]
	v_pk_mul_f32 v[10:11], v[10:11], v[152:153]
	v_pk_add_f32 v[12:13], v[218:219], v[6:7]
	v_pk_fma_f32 v[16:17], v[10:11], v[12:13], v[186:187]
	v_cvt_pk_bf16_f32 v28, v14, v15
	v_cvt_pk_bf16_f32 v29, v16, v17
	global_store_dwordx2 v2, v[28:29], s[26:27] offset:2560
	v_pk_mul_f32 v[10:11], v[90:91], v[4:5]
	v_pk_mul_f32 v[10:11], v[10:11], v[156:157]
	v_pk_add_f32 v[12:13], v[220:221], v[6:7]
	v_pk_fma_f32 v[14:15], v[10:11], v[12:13], v[188:189]
	v_pk_mul_f32 v[10:11], v[92:93], v[4:5]
	v_pk_mul_f32 v[10:11], v[10:11], v[158:159]
	v_pk_add_f32 v[12:13], v[222:223], v[6:7]
	v_pk_fma_f32 v[16:17], v[10:11], v[12:13], v[190:191]
	v_cvt_pk_bf16_f32 v30, v14, v15
	v_cvt_pk_bf16_f32 v31, v16, v17
	global_store_dwordx2 v2, v[30:31], s[26:27] offset:3072
	v_pk_mul_f32 v[10:11], v[94:95], v[4:5]
	v_pk_mul_f32 v[10:11], v[10:11], v[160:161]
	v_pk_add_f32 v[12:13], v[224:225], v[6:7]
	v_pk_fma_f32 v[14:15], v[10:11], v[12:13], v[192:193]
	v_pk_mul_f32 v[10:11], v[96:97], v[4:5]
	v_pk_mul_f32 v[10:11], v[10:11], v[162:163]
	v_pk_add_f32 v[12:13], v[226:227], v[6:7]
	v_pk_fma_f32 v[16:17], v[10:11], v[12:13], v[194:195]
	v_cvt_pk_bf16_f32 v32, v14, v15
	v_cvt_pk_bf16_f32 v33, v16, v17
	global_store_dwordx2 v2, v[32:33], s[26:27] offset:3584
	s_waitcnt vmcnt(0)
	s_branch .Ltrp1_B2
.Ltrp1_B2:
	s_load_dwordx2 s[0:1], s[92:93], 0x58
	s_load_dwordx2 s[2:3], s[92:93], 0xb8
	s_load_dwordx2 s[4:5], s[92:93], 0xc0
	s_load_dwordx2 s[6:7], s[92:93], 0xc8
	s_load_dwordx2 s[8:9], s[92:93], 0xd0
	s_load_dwordx2 s[10:11], s[92:93], 0xe8
	v_and_b32_e32 v74, 63, v154
	v_lshrrev_b32_e32 v75, 6, v154
	v_mul_u32_u24_e32 v75, 0x2100, v75
	v_lshrrev_b32_e32 v3, 5, v74
	v_and_b32_e32 v4, 31, v74
	v_lshlrev_b32_e32 v4, 2, v4
	v_lshrrev_b32_e32 v5, 3, v74
	v_and_b32_e32 v6, 7, v74
	v_mul_u32_u24_e32 v2, 264, v6
	v_add_u32_e32 v2, v2, v5
	v_lshl_add_u32 v2, v2, 2, v75
	v_lshlrev_b32_e32 v6, 4, v6
	v_mul_u32_u24_e32 v1, 132, v5
	v_add3_u32 v1, v1, v6, v75
	v_readfirstlane_b32 s13, v154
	s_lshr_b32 s13, s13, 6
	s_lshl_b32 s26, s96, 3
	s_add_u32 s13, s13, s26
	s_mov_b32 s12, s13
	s_waitcnt lgkmcnt(0)
	s_cmp_ge_u32 s12, 12288
	s_cbranch_scc1 .Ltrc_done
	s_cmp_ge_u32 s12, 33280
	s_cselect_b32 s41, 1, 0
	s_cselect_b32 s26, 33280, 0
	s_sub_u32 s42, s12, s26
	s_cmp_ge_u32 s42, 12288
	s_cbranch_scc1 .Ltrc_m2
	s_mul_i32 s43, s42, 43691
	s_lshr_b32 s43, s43, 24
	s_mul_i32 s26, s43, 384
	s_sub_u32 s44, s42, s26
	s_mov_b32 s14, s0
	s_mov_b32 s15, s1
	s_mov_b32 s36, 0xc000
	s_mov_b32 s37, 0x6000000
	s_mov_b32 s38, 0x0
	s_mov_b32 s39, 0x3000000
	s_mov_b32 s40, 0x1000
	s_branch .Ltrc_dec_done1
